# input-projection epilogue for transposed outputs (a_v, c_v, d_v): bf16 tile transposed through a wave-private LDS image and written with 16-byte stores instead of 2-byte stores
# baseline (speedup 1.0000x reference)
.LBB0_386:
	s_and_b64 vcc, exec, s[2:3]
	s_cbranch_vccz .LBB0_586
	v_readfirstlane_b32 s22, v196
	v_readlane_b32 s50, v249, 6
	v_readlane_b32 s51, v249, 7
	v_readlane_b32 s86, v250, 58
	s_nop 3
	s_sub_i32 s23, s22, 0x8000
	s_lshr_b32 s23, s23, 6
	s_lshr_b32 s28, s22, 11
	s_and_b32 s29, s22, 0x7ff
	s_and_b32 s31, s74, 1
	s_lshl_b32 s31, s31, 8
	s_lshl_b32 s35, s63, 5
	s_add_i32 s31, s31, s35
	s_lshl_b32 s38, s86, 20
	s_lshl_b32 s39, s86, 26
	s_cmp_lg_u64 s[42:43], 0
	s_cselect_b32 s28, s23, s28
	s_cselect_b32 s29, 0, s29
	s_cselect_b32 s23, 2, 0
	s_cselect_b32 s35, 0, 0x80
	s_cselect_b32 s38, s38, s39
	s_mov_b32 s39, 0x189e0000
	s_cselect_b32 s39, s39, 0x10200000
	s_cselect_b32 s86, 0x8000, 0
	s_add_u32 s48, s26, s39
	s_addc_u32 s49, s27, 0
	s_add_u32 s48, s48, s38
	s_addc_u32 s49, s49, 0
	s_cmp_lg_u64 s[42:43], 0
	s_cselect_b32 s38, 0x2000000, 0
	s_movk_i32 s39, 0x1000
	s_cselect_b32 s39, 0x80, s39
	s_cmp_gt_u32 s74, 9
	s_cbranch_scc1 .Ltr_k2
	s_cmp_gt_u32 s74, 3
	s_cbranch_scc1 .Ltr_k1
	s_add_u32 s44, s67, s38
	s_addc_u32 s45, s68, 0
	s_mov_b32 s100, 0
	s_lshl_b32 s101, s28, 9
	s_add_i32 s101, s101, s31
	s_mul_i32 s101, s101, s39
	s_add_i32 s101, s101, s100
	s_lshl_b32 s38, s29, 1
	s_add_i32 s101, s101, s38
	s_add_i32 s28, s28, s23
	s_add_i32 s29, s29, s35
	s_lshl_b32 s38, s28, 9
	s_add_i32 s38, s38, s31
	s_mul_i32 s38, s38, s39
	s_add_i32 s38, s38, s100
	s_lshl_b32 s28, s29, 1
	s_add_i32 s38, s38, s28
	s_lshl_b32 s100, s39, 7
	v_lshrrev_b32_e32 v244, 6, v224
	v_mul_u32_u24_e32 v244, 2560, v244
	v_add_u32_e32 v244, 0x20000, v244
	v_mul_u32_u24_e32 v208, 320, v239
	v_lshl_add_u32 v208, v238, 1, v208
	v_add_u32_e32 v208, v208, v244
	v_and_b32_e32 v210, 63, v229
	v_lshrrev_b32_e32 v211, 2, v210
	v_and_b32_e32 v210, 3, v210
	v_mul_u32_u24_e32 v209, 80, v211
	v_lshl_add_u32 v209, v210, 4, v209
	v_add_u32_e32 v209, v209, v244
	v_mul_lo_u32 v211, v211, s39
	v_lshl_add_u32 v210, v210, 4, v211
	s_lshl_b32 s28, s39, 4
	v_add_u32_e32 v211, s28, v210
	v_lshlrev_b32_e32 v221, 2, v196
	v_xor_b32_e32 v242, 16, v229
	v_xor_b32_e32 v243, 32, v229
	v_lshlrev_b32_e32 v242, 2, v242
	v_lshlrev_b32_e32 v243, 2, v243
	v_pk_mul_f32 v[128:129], v[124:125], v[194:195] op_sel_hi:[1,0]
	v_pk_mul_f32 v[130:131], v[126:127], v[194:195] op_sel_hi:[1,0]
	v_mul_f32_e32 v134, 0x3d372713, v128
	v_mul_f32_e32 v135, 0x3d372713, v129
	v_mul_f32_e32 v136, 0x3d372713, v130
	v_mul_f32_e32 v137, 0x3d372713, v131
	v_mul_f32_e32 v134, v128, v134
	v_mul_f32_e32 v135, v129, v135
	v_mul_f32_e32 v136, v130, v136
	v_mul_f32_e32 v137, v131, v137
	v_fma_f32 v134, v128, v134, v128
	v_fma_f32 v135, v129, v135, v129
	v_fma_f32 v136, v130, v136, v130
	v_fma_f32 v137, v131, v137, v131
	v_mul_f32_e32 v134, 0x3fcc422a, v134
	v_mul_f32_e32 v135, 0x3fcc422a, v135
	v_mul_f32_e32 v136, 0x3fcc422a, v136
	v_mul_f32_e32 v137, 0x3fcc422a, v137
	v_mul_f32_e32 v134, 0xbfb8aa3b, v134
	v_mul_f32_e32 v135, 0xbfb8aa3b, v135
	v_mul_f32_e32 v136, 0xbfb8aa3b, v136
	v_mul_f32_e32 v137, 0xbfb8aa3b, v137
	v_exp_f32_e32 v134, v134
	v_exp_f32_e32 v135, v135
	v_exp_f32_e32 v136, v136
	v_exp_f32_e32 v137, v137
	v_add_f32_e32 v134, 1.0, v134
	v_add_f32_e32 v135, 1.0, v135
	v_add_f32_e32 v136, 1.0, v136
	v_add_f32_e32 v137, 1.0, v137
	v_rcp_f32_e32 v134, v134
	v_rcp_f32_e32 v135, v135
	v_rcp_f32_e32 v136, v136
	v_rcp_f32_e32 v137, v137
	s_nop 0
	v_pk_mul_f32 v[128:129], v[128:129], v[134:135]
	v_pk_mul_f32 v[130:131], v[130:131], v[136:137]
	v_mul_f32_e32 v200, v128, v128
	v_fmac_f32_e32 v200, v129, v129
	v_fmac_f32_e32 v200, v130, v130
	v_fmac_f32_e32 v200, v131, v131
	v_cvt_pk_bf16_f32 v132, v128, v129
	v_cvt_pk_bf16_f32 v133, v130, v131
	ds_write_b16 v208, v132
	ds_write_b16_d16_hi v208, v132 offset:80
	ds_write_b16 v208, v133 offset:160
	ds_write_b16_d16_hi v208, v133 offset:240
	v_pk_mul_f32 v[128:129], v[120:121], v[194:195] op_sel_hi:[1,0]
	v_pk_mul_f32 v[130:131], v[122:123], v[194:195] op_sel_hi:[1,0]
	v_mul_f32_e32 v134, 0x3d372713, v128
	v_mul_f32_e32 v135, 0x3d372713, v129
	v_mul_f32_e32 v136, 0x3d372713, v130
	v_mul_f32_e32 v137, 0x3d372713, v131
	v_mul_f32_e32 v134, v128, v134
	v_mul_f32_e32 v135, v129, v135
	v_mul_f32_e32 v136, v130, v136
	v_mul_f32_e32 v137, v131, v137
	v_fma_f32 v134, v128, v134, v128
	v_fma_f32 v135, v129, v135, v129
	v_fma_f32 v136, v130, v136, v130
	v_fma_f32 v137, v131, v137, v131
	v_mul_f32_e32 v134, 0x3fcc422a, v134
	v_mul_f32_e32 v135, 0x3fcc422a, v135
	v_mul_f32_e32 v136, 0x3fcc422a, v136
	v_mul_f32_e32 v137, 0x3fcc422a, v137
	v_mul_f32_e32 v134, 0xbfb8aa3b, v134
	v_mul_f32_e32 v135, 0xbfb8aa3b, v135
	v_mul_f32_e32 v136, 0xbfb8aa3b, v136
	v_mul_f32_e32 v137, 0xbfb8aa3b, v137
	v_exp_f32_e32 v134, v134
	v_exp_f32_e32 v135, v135
	v_exp_f32_e32 v136, v136
	v_exp_f32_e32 v137, v137
	v_add_f32_e32 v134, 1.0, v134
	v_add_f32_e32 v135, 1.0, v135
	v_add_f32_e32 v136, 1.0, v136
	v_add_f32_e32 v137, 1.0, v137
	v_rcp_f32_e32 v134, v134
	v_rcp_f32_e32 v135, v135
	v_rcp_f32_e32 v136, v136
	v_rcp_f32_e32 v137, v137
	s_nop 0
	v_pk_mul_f32 v[128:129], v[128:129], v[134:135]
	v_pk_mul_f32 v[130:131], v[130:131], v[136:137]
	v_fmac_f32_e32 v200, v128, v128
	v_fmac_f32_e32 v200, v129, v129
	v_fmac_f32_e32 v200, v130, v130
	v_fmac_f32_e32 v200, v131, v131
	v_cvt_pk_bf16_f32 v132, v128, v129
	v_cvt_pk_bf16_f32 v133, v130, v131
	ds_write_b16 v208, v132 offset:1280
	ds_write_b16_d16_hi v208, v132 offset:1360
	ds_write_b16 v208, v133 offset:1440
	ds_write_b16_d16_hi v208, v133 offset:1520
	v_pk_mul_f32 v[128:129], v[108:109], v[190:191] op_sel_hi:[1,0]
	v_pk_mul_f32 v[130:131], v[110:111], v[190:191] op_sel_hi:[1,0]
	v_mul_f32_e32 v134, 0x3d372713, v128
	v_mul_f32_e32 v135, 0x3d372713, v129
	v_mul_f32_e32 v136, 0x3d372713, v130
	v_mul_f32_e32 v137, 0x3d372713, v131
	v_mul_f32_e32 v134, v128, v134
	v_mul_f32_e32 v135, v129, v135
	v_mul_f32_e32 v136, v130, v136
	v_mul_f32_e32 v137, v131, v137
	v_fma_f32 v134, v128, v134, v128
	v_fma_f32 v135, v129, v135, v129
	v_fma_f32 v136, v130, v136, v130
	v_fma_f32 v137, v131, v137, v131
	v_mul_f32_e32 v134, 0x3fcc422a, v134
	v_mul_f32_e32 v135, 0x3fcc422a, v135
	v_mul_f32_e32 v136, 0x3fcc422a, v136
	v_mul_f32_e32 v137, 0x3fcc422a, v137
	v_mul_f32_e32 v134, 0xbfb8aa3b, v134
	v_mul_f32_e32 v135, 0xbfb8aa3b, v135
	v_mul_f32_e32 v136, 0xbfb8aa3b, v136
	v_mul_f32_e32 v137, 0xbfb8aa3b, v137
	v_exp_f32_e32 v134, v134
	v_exp_f32_e32 v135, v135
	v_exp_f32_e32 v136, v136
	v_exp_f32_e32 v137, v137
	v_add_f32_e32 v134, 1.0, v134
	v_add_f32_e32 v135, 1.0, v135
	v_add_f32_e32 v136, 1.0, v136
	v_add_f32_e32 v137, 1.0, v137
	v_rcp_f32_e32 v134, v134
	v_rcp_f32_e32 v135, v135
	v_rcp_f32_e32 v136, v136
	v_rcp_f32_e32 v137, v137
	s_nop 0
	v_pk_mul_f32 v[128:129], v[128:129], v[134:135]
	v_pk_mul_f32 v[130:131], v[130:131], v[136:137]
	v_mul_f32_e32 v201, v128, v128
	v_fmac_f32_e32 v201, v129, v129
	v_fmac_f32_e32 v201, v130, v130
	v_fmac_f32_e32 v201, v131, v131
	v_cvt_pk_bf16_f32 v132, v128, v129
	v_cvt_pk_bf16_f32 v133, v130, v131
	ds_write_b16 v208, v132 offset:32
	ds_write_b16_d16_hi v208, v132 offset:112
	ds_write_b16 v208, v133 offset:192
	ds_write_b16_d16_hi v208, v133 offset:272
	v_pk_mul_f32 v[128:129], v[104:105], v[190:191] op_sel_hi:[1,0]
	v_pk_mul_f32 v[130:131], v[106:107], v[190:191] op_sel_hi:[1,0]
	v_mul_f32_e32 v134, 0x3d372713, v128
	v_mul_f32_e32 v135, 0x3d372713, v129
	v_mul_f32_e32 v136, 0x3d372713, v130
	v_mul_f32_e32 v137, 0x3d372713, v131
	v_mul_f32_e32 v134, v128, v134
	v_mul_f32_e32 v135, v129, v135
	v_mul_f32_e32 v136, v130, v136
	v_mul_f32_e32 v137, v131, v137
	v_fma_f32 v134, v128, v134, v128
	v_fma_f32 v135, v129, v135, v129
	v_fma_f32 v136, v130, v136, v130
	v_fma_f32 v137, v131, v137, v131
	v_mul_f32_e32 v134, 0x3fcc422a, v134
	v_mul_f32_e32 v135, 0x3fcc422a, v135
	v_mul_f32_e32 v136, 0x3fcc422a, v136
	v_mul_f32_e32 v137, 0x3fcc422a, v137
	v_mul_f32_e32 v134, 0xbfb8aa3b, v134
	v_mul_f32_e32 v135, 0xbfb8aa3b, v135
	v_mul_f32_e32 v136, 0xbfb8aa3b, v136
	v_mul_f32_e32 v137, 0xbfb8aa3b, v137
	v_exp_f32_e32 v134, v134
	v_exp_f32_e32 v135, v135
	v_exp_f32_e32 v136, v136
	v_exp_f32_e32 v137, v137
	v_add_f32_e32 v134, 1.0, v134
	v_add_f32_e32 v135, 1.0, v135
	v_add_f32_e32 v136, 1.0, v136
	v_add_f32_e32 v137, 1.0, v137
	v_rcp_f32_e32 v134, v134
	v_rcp_f32_e32 v135, v135
	v_rcp_f32_e32 v136, v136
	v_rcp_f32_e32 v137, v137
	s_nop 0
	v_pk_mul_f32 v[128:129], v[128:129], v[134:135]
	v_pk_mul_f32 v[130:131], v[130:131], v[136:137]
	v_fmac_f32_e32 v201, v128, v128
	v_fmac_f32_e32 v201, v129, v129
	v_fmac_f32_e32 v201, v130, v130
	v_fmac_f32_e32 v201, v131, v131
	v_cvt_pk_bf16_f32 v132, v128, v129
	v_cvt_pk_bf16_f32 v133, v130, v131
	ds_write_b16 v208, v132 offset:1312
	ds_write_b16_d16_hi v208, v132 offset:1392
	ds_write_b16 v208, v133 offset:1472
	ds_write_b16_d16_hi v208, v133 offset:1552
	s_waitcnt lgkmcnt(0)
	ds_read_b128 v[212:215], v209
	ds_read_b128 v[216:219], v209 offset:1280
	s_add_u32 s46, s44, s101
	s_addc_u32 s47, s45, 0
	s_waitcnt lgkmcnt(0)
	global_store_dwordx4 v210, v[212:215], s[46:47]
	global_store_dwordx4 v211, v[216:219], s[46:47]
	v_pk_mul_f32 v[128:129], v[92:93], v[172:173] op_sel_hi:[1,0]
	v_pk_mul_f32 v[130:131], v[94:95], v[172:173] op_sel_hi:[1,0]
	v_mul_f32_e32 v134, 0x3d372713, v128
	v_mul_f32_e32 v135, 0x3d372713, v129
	v_mul_f32_e32 v136, 0x3d372713, v130
	v_mul_f32_e32 v137, 0x3d372713, v131
	v_mul_f32_e32 v134, v128, v134
	v_mul_f32_e32 v135, v129, v135
	v_mul_f32_e32 v136, v130, v136
	v_mul_f32_e32 v137, v131, v137
	v_fma_f32 v134, v128, v134, v128
	v_fma_f32 v135, v129, v135, v129
	v_fma_f32 v136, v130, v136, v130
	v_fma_f32 v137, v131, v137, v131
	v_mul_f32_e32 v134, 0x3fcc422a, v134
	v_mul_f32_e32 v135, 0x3fcc422a, v135
	v_mul_f32_e32 v136, 0x3fcc422a, v136
	v_mul_f32_e32 v137, 0x3fcc422a, v137
	v_mul_f32_e32 v134, 0xbfb8aa3b, v134
	v_mul_f32_e32 v135, 0xbfb8aa3b, v135
	v_mul_f32_e32 v136, 0xbfb8aa3b, v136
	v_mul_f32_e32 v137, 0xbfb8aa3b, v137
	v_exp_f32_e32 v134, v134
	v_exp_f32_e32 v135, v135
	v_exp_f32_e32 v136, v136
	v_exp_f32_e32 v137, v137
	v_add_f32_e32 v134, 1.0, v134
	v_add_f32_e32 v135, 1.0, v135
	v_add_f32_e32 v136, 1.0, v136
	v_add_f32_e32 v137, 1.0, v137
	v_rcp_f32_e32 v134, v134
	v_rcp_f32_e32 v135, v135
	v_rcp_f32_e32 v136, v136
	v_rcp_f32_e32 v137, v137
	s_nop 0
	v_pk_mul_f32 v[128:129], v[128:129], v[134:135]
	v_pk_mul_f32 v[130:131], v[130:131], v[136:137]
	v_mul_f32_e32 v202, v128, v128
	v_fmac_f32_e32 v202, v129, v129
	v_fmac_f32_e32 v202, v130, v130
	v_fmac_f32_e32 v202, v131, v131
	v_cvt_pk_bf16_f32 v132, v128, v129
	v_cvt_pk_bf16_f32 v133, v130, v131
	ds_write_b16 v208, v132
	ds_write_b16_d16_hi v208, v132 offset:80
	ds_write_b16 v208, v133 offset:160
	ds_write_b16_d16_hi v208, v133 offset:240
	v_pk_mul_f32 v[128:129], v[88:89], v[172:173] op_sel_hi:[1,0]
	v_pk_mul_f32 v[130:131], v[90:91], v[172:173] op_sel_hi:[1,0]
	v_mul_f32_e32 v134, 0x3d372713, v128
	v_mul_f32_e32 v135, 0x3d372713, v129
	v_mul_f32_e32 v136, 0x3d372713, v130
	v_mul_f32_e32 v137, 0x3d372713, v131
	v_mul_f32_e32 v134, v128, v134
	v_mul_f32_e32 v135, v129, v135
	v_mul_f32_e32 v136, v130, v136
	v_mul_f32_e32 v137, v131, v137
	v_fma_f32 v134, v128, v134, v128
	v_fma_f32 v135, v129, v135, v129
	v_fma_f32 v136, v130, v136, v130
	v_fma_f32 v137, v131, v137, v131
	v_mul_f32_e32 v134, 0x3fcc422a, v134
	v_mul_f32_e32 v135, 0x3fcc422a, v135
	v_mul_f32_e32 v136, 0x3fcc422a, v136
	v_mul_f32_e32 v137, 0x3fcc422a, v137
	v_mul_f32_e32 v134, 0xbfb8aa3b, v134
	v_mul_f32_e32 v135, 0xbfb8aa3b, v135
	v_mul_f32_e32 v136, 0xbfb8aa3b, v136
	v_mul_f32_e32 v137, 0xbfb8aa3b, v137
	v_exp_f32_e32 v134, v134
	v_exp_f32_e32 v135, v135
	v_exp_f32_e32 v136, v136
	v_exp_f32_e32 v137, v137
	v_add_f32_e32 v134, 1.0, v134
	v_add_f32_e32 v135, 1.0, v135
	v_add_f32_e32 v136, 1.0, v136
	v_add_f32_e32 v137, 1.0, v137
	v_rcp_f32_e32 v134, v134
	v_rcp_f32_e32 v135, v135
	v_rcp_f32_e32 v136, v136
	v_rcp_f32_e32 v137, v137
	s_nop 0
	v_pk_mul_f32 v[128:129], v[128:129], v[134:135]
	v_pk_mul_f32 v[130:131], v[130:131], v[136:137]
	v_fmac_f32_e32 v202, v128, v128
	v_fmac_f32_e32 v202, v129, v129
	v_fmac_f32_e32 v202, v130, v130
	v_fmac_f32_e32 v202, v131, v131
	v_cvt_pk_bf16_f32 v132, v128, v129
	v_cvt_pk_bf16_f32 v133, v130, v131
	ds_write_b16 v208, v132 offset:1280
	ds_write_b16_d16_hi v208, v132 offset:1360
	ds_write_b16 v208, v133 offset:1440
	ds_write_b16_d16_hi v208, v133 offset:1520
	v_pk_mul_f32 v[128:129], v[76:77], v[168:169] op_sel_hi:[1,0]
	v_pk_mul_f32 v[130:131], v[78:79], v[168:169] op_sel_hi:[1,0]
	v_mul_f32_e32 v134, 0x3d372713, v128
	v_mul_f32_e32 v135, 0x3d372713, v129
	v_mul_f32_e32 v136, 0x3d372713, v130
	v_mul_f32_e32 v137, 0x3d372713, v131
	v_mul_f32_e32 v134, v128, v134
	v_mul_f32_e32 v135, v129, v135
	v_mul_f32_e32 v136, v130, v136
	v_mul_f32_e32 v137, v131, v137
	v_fma_f32 v134, v128, v134, v128
	v_fma_f32 v135, v129, v135, v129
	v_fma_f32 v136, v130, v136, v130
	v_fma_f32 v137, v131, v137, v131
	v_mul_f32_e32 v134, 0x3fcc422a, v134
	v_mul_f32_e32 v135, 0x3fcc422a, v135
	v_mul_f32_e32 v136, 0x3fcc422a, v136
	v_mul_f32_e32 v137, 0x3fcc422a, v137
	v_mul_f32_e32 v134, 0xbfb8aa3b, v134
	v_mul_f32_e32 v135, 0xbfb8aa3b, v135
	v_mul_f32_e32 v136, 0xbfb8aa3b, v136
	v_mul_f32_e32 v137, 0xbfb8aa3b, v137
	v_exp_f32_e32 v134, v134
	v_exp_f32_e32 v135, v135
	v_exp_f32_e32 v136, v136
	v_exp_f32_e32 v137, v137
	v_add_f32_e32 v134, 1.0, v134
	v_add_f32_e32 v135, 1.0, v135
	v_add_f32_e32 v136, 1.0, v136
	v_add_f32_e32 v137, 1.0, v137
	v_rcp_f32_e32 v134, v134
	v_rcp_f32_e32 v135, v135
	v_rcp_f32_e32 v136, v136
	v_rcp_f32_e32 v137, v137
	s_nop 0
	v_pk_mul_f32 v[128:129], v[128:129], v[134:135]
	v_pk_mul_f32 v[130:131], v[130:131], v[136:137]
	v_mul_f32_e32 v203, v128, v128
	v_fmac_f32_e32 v203, v129, v129
	v_fmac_f32_e32 v203, v130, v130
	v_fmac_f32_e32 v203, v131, v131
	v_cvt_pk_bf16_f32 v132, v128, v129
	v_cvt_pk_bf16_f32 v133, v130, v131
	ds_write_b16 v208, v132 offset:32
	ds_write_b16_d16_hi v208, v132 offset:112
	ds_write_b16 v208, v133 offset:192
	ds_write_b16_d16_hi v208, v133 offset:272
	v_pk_mul_f32 v[128:129], v[72:73], v[168:169] op_sel_hi:[1,0]
	v_pk_mul_f32 v[130:131], v[74:75], v[168:169] op_sel_hi:[1,0]
	v_mul_f32_e32 v134, 0x3d372713, v128
	v_mul_f32_e32 v135, 0x3d372713, v129
	v_mul_f32_e32 v136, 0x3d372713, v130
	v_mul_f32_e32 v137, 0x3d372713, v131
	v_mul_f32_e32 v134, v128, v134
	v_mul_f32_e32 v135, v129, v135
	v_mul_f32_e32 v136, v130, v136
	v_mul_f32_e32 v137, v131, v137
	v_fma_f32 v134, v128, v134, v128
	v_fma_f32 v135, v129, v135, v129
	v_fma_f32 v136, v130, v136, v130
	v_fma_f32 v137, v131, v137, v131
	v_mul_f32_e32 v134, 0x3fcc422a, v134
	v_mul_f32_e32 v135, 0x3fcc422a, v135
	v_mul_f32_e32 v136, 0x3fcc422a, v136
	v_mul_f32_e32 v137, 0x3fcc422a, v137
	v_mul_f32_e32 v134, 0xbfb8aa3b, v134
	v_mul_f32_e32 v135, 0xbfb8aa3b, v135
	v_mul_f32_e32 v136, 0xbfb8aa3b, v136
	v_mul_f32_e32 v137, 0xbfb8aa3b, v137
	v_exp_f32_e32 v134, v134
	v_exp_f32_e32 v135, v135
	v_exp_f32_e32 v136, v136
	v_exp_f32_e32 v137, v137
	v_add_f32_e32 v134, 1.0, v134
	v_add_f32_e32 v135, 1.0, v135
	v_add_f32_e32 v136, 1.0, v136
	v_add_f32_e32 v137, 1.0, v137
	v_rcp_f32_e32 v134, v134
	v_rcp_f32_e32 v135, v135
	v_rcp_f32_e32 v136, v136
	v_rcp_f32_e32 v137, v137
	s_nop 0
	v_pk_mul_f32 v[128:129], v[128:129], v[134:135]
	v_pk_mul_f32 v[130:131], v[130:131], v[136:137]
	v_fmac_f32_e32 v203, v128, v128
	v_fmac_f32_e32 v203, v129, v129
	v_fmac_f32_e32 v203, v130, v130
	v_fmac_f32_e32 v203, v131, v131
	v_cvt_pk_bf16_f32 v132, v128, v129
	v_cvt_pk_bf16_f32 v133, v130, v131
	ds_write_b16 v208, v132 offset:1312
	ds_write_b16_d16_hi v208, v132 offset:1392
	ds_write_b16 v208, v133 offset:1472
	ds_write_b16_d16_hi v208, v133 offset:1552
	s_waitcnt lgkmcnt(0)
	ds_read_b128 v[212:215], v209
	ds_read_b128 v[216:219], v209 offset:1280
	s_add_u32 s46, s44, s101
	s_addc_u32 s47, s45, 0
	s_waitcnt lgkmcnt(0)
	global_store_dwordx4 v210, v[212:215], s[46:47] offset:64
	global_store_dwordx4 v211, v[216:219], s[46:47] offset:64
	v_pk_mul_f32 v[128:129], v[116:117], v[194:195] op_sel_hi:[1,0]
	v_pk_mul_f32 v[130:131], v[118:119], v[194:195] op_sel_hi:[1,0]
	v_mul_f32_e32 v134, 0x3d372713, v128
	v_mul_f32_e32 v135, 0x3d372713, v129
	v_mul_f32_e32 v136, 0x3d372713, v130
	v_mul_f32_e32 v137, 0x3d372713, v131
	v_mul_f32_e32 v134, v128, v134
	v_mul_f32_e32 v135, v129, v135
	v_mul_f32_e32 v136, v130, v136
	v_mul_f32_e32 v137, v131, v137
	v_fma_f32 v134, v128, v134, v128
	v_fma_f32 v135, v129, v135, v129
	v_fma_f32 v136, v130, v136, v130
	v_fma_f32 v137, v131, v137, v131
	v_mul_f32_e32 v134, 0x3fcc422a, v134
	v_mul_f32_e32 v135, 0x3fcc422a, v135
	v_mul_f32_e32 v136, 0x3fcc422a, v136
	v_mul_f32_e32 v137, 0x3fcc422a, v137
	v_mul_f32_e32 v134, 0xbfb8aa3b, v134
	v_mul_f32_e32 v135, 0xbfb8aa3b, v135
	v_mul_f32_e32 v136, 0xbfb8aa3b, v136
	v_mul_f32_e32 v137, 0xbfb8aa3b, v137
	v_exp_f32_e32 v134, v134
	v_exp_f32_e32 v135, v135
	v_exp_f32_e32 v136, v136
	v_exp_f32_e32 v137, v137
	v_add_f32_e32 v134, 1.0, v134
	v_add_f32_e32 v135, 1.0, v135
	v_add_f32_e32 v136, 1.0, v136
	v_add_f32_e32 v137, 1.0, v137
	v_rcp_f32_e32 v134, v134
	v_rcp_f32_e32 v135, v135
	v_rcp_f32_e32 v136, v136
	v_rcp_f32_e32 v137, v137
	s_nop 0
	v_pk_mul_f32 v[128:129], v[128:129], v[134:135]
	v_pk_mul_f32 v[130:131], v[130:131], v[136:137]
	v_fmac_f32_e32 v200, v128, v128
	v_fmac_f32_e32 v200, v129, v129
	v_fmac_f32_e32 v200, v130, v130
	v_fmac_f32_e32 v200, v131, v131
	v_cvt_pk_bf16_f32 v132, v128, v129
	v_cvt_pk_bf16_f32 v133, v130, v131
	ds_write_b16 v208, v132
	ds_write_b16_d16_hi v208, v132 offset:80
	ds_write_b16 v208, v133 offset:160
	ds_write_b16_d16_hi v208, v133 offset:240
	v_pk_mul_f32 v[128:129], v[112:113], v[194:195] op_sel_hi:[1,0]
	v_pk_mul_f32 v[130:131], v[114:115], v[194:195] op_sel_hi:[1,0]
	v_mul_f32_e32 v134, 0x3d372713, v128
	v_mul_f32_e32 v135, 0x3d372713, v129
	v_mul_f32_e32 v136, 0x3d372713, v130
	v_mul_f32_e32 v137, 0x3d372713, v131
	v_mul_f32_e32 v134, v128, v134
	v_mul_f32_e32 v135, v129, v135
	v_mul_f32_e32 v136, v130, v136
	v_mul_f32_e32 v137, v131, v137
	v_fma_f32 v134, v128, v134, v128
	v_fma_f32 v135, v129, v135, v129
	v_fma_f32 v136, v130, v136, v130
	v_fma_f32 v137, v131, v137, v131
	v_mul_f32_e32 v134, 0x3fcc422a, v134
	v_mul_f32_e32 v135, 0x3fcc422a, v135
	v_mul_f32_e32 v136, 0x3fcc422a, v136
	v_mul_f32_e32 v137, 0x3fcc422a, v137
	v_mul_f32_e32 v134, 0xbfb8aa3b, v134
	v_mul_f32_e32 v135, 0xbfb8aa3b, v135
	v_mul_f32_e32 v136, 0xbfb8aa3b, v136
	v_mul_f32_e32 v137, 0xbfb8aa3b, v137
	v_exp_f32_e32 v134, v134
	v_exp_f32_e32 v135, v135
	v_exp_f32_e32 v136, v136
	v_exp_f32_e32 v137, v137
	v_add_f32_e32 v134, 1.0, v134
	v_add_f32_e32 v135, 1.0, v135
	v_add_f32_e32 v136, 1.0, v136
	v_add_f32_e32 v137, 1.0, v137
	v_rcp_f32_e32 v134, v134
	v_rcp_f32_e32 v135, v135
	v_rcp_f32_e32 v136, v136
	v_rcp_f32_e32 v137, v137
	s_nop 0
	v_pk_mul_f32 v[128:129], v[128:129], v[134:135]
	v_pk_mul_f32 v[130:131], v[130:131], v[136:137]
	v_fmac_f32_e32 v200, v128, v128
	v_fmac_f32_e32 v200, v129, v129
	v_fmac_f32_e32 v200, v130, v130
	v_fmac_f32_e32 v200, v131, v131
	v_cvt_pk_bf16_f32 v132, v128, v129
	v_cvt_pk_bf16_f32 v133, v130, v131
	ds_write_b16 v208, v132 offset:1280
	ds_write_b16_d16_hi v208, v132 offset:1360
	ds_write_b16 v208, v133 offset:1440
	ds_write_b16_d16_hi v208, v133 offset:1520
	v_pk_mul_f32 v[128:129], v[100:101], v[190:191] op_sel_hi:[1,0]
	v_pk_mul_f32 v[130:131], v[102:103], v[190:191] op_sel_hi:[1,0]
	v_mul_f32_e32 v134, 0x3d372713, v128
	v_mul_f32_e32 v135, 0x3d372713, v129
	v_mul_f32_e32 v136, 0x3d372713, v130
	v_mul_f32_e32 v137, 0x3d372713, v131
	v_mul_f32_e32 v134, v128, v134
	v_mul_f32_e32 v135, v129, v135
	v_mul_f32_e32 v136, v130, v136
	v_mul_f32_e32 v137, v131, v137
	v_fma_f32 v134, v128, v134, v128
	v_fma_f32 v135, v129, v135, v129
	v_fma_f32 v136, v130, v136, v130
	v_fma_f32 v137, v131, v137, v131
	v_mul_f32_e32 v134, 0x3fcc422a, v134
	v_mul_f32_e32 v135, 0x3fcc422a, v135
	v_mul_f32_e32 v136, 0x3fcc422a, v136
	v_mul_f32_e32 v137, 0x3fcc422a, v137
	v_mul_f32_e32 v134, 0xbfb8aa3b, v134
	v_mul_f32_e32 v135, 0xbfb8aa3b, v135
	v_mul_f32_e32 v136, 0xbfb8aa3b, v136
	v_mul_f32_e32 v137, 0xbfb8aa3b, v137
	v_exp_f32_e32 v134, v134
	v_exp_f32_e32 v135, v135
	v_exp_f32_e32 v136, v136
	v_exp_f32_e32 v137, v137
	v_add_f32_e32 v134, 1.0, v134
	v_add_f32_e32 v135, 1.0, v135
	v_add_f32_e32 v136, 1.0, v136
	v_add_f32_e32 v137, 1.0, v137
	v_rcp_f32_e32 v134, v134
	v_rcp_f32_e32 v135, v135
	v_rcp_f32_e32 v136, v136
	v_rcp_f32_e32 v137, v137
	s_nop 0
	v_pk_mul_f32 v[128:129], v[128:129], v[134:135]
	v_pk_mul_f32 v[130:131], v[130:131], v[136:137]
	v_fmac_f32_e32 v201, v128, v128
	v_fmac_f32_e32 v201, v129, v129
	v_fmac_f32_e32 v201, v130, v130
	v_fmac_f32_e32 v201, v131, v131
	v_cvt_pk_bf16_f32 v132, v128, v129
	v_cvt_pk_bf16_f32 v133, v130, v131
	ds_write_b16 v208, v132 offset:32
	ds_write_b16_d16_hi v208, v132 offset:112
	ds_write_b16 v208, v133 offset:192
	ds_write_b16_d16_hi v208, v133 offset:272
	v_pk_mul_f32 v[128:129], v[96:97], v[190:191] op_sel_hi:[1,0]
	v_pk_mul_f32 v[130:131], v[98:99], v[190:191] op_sel_hi:[1,0]
	v_mul_f32_e32 v134, 0x3d372713, v128
	v_mul_f32_e32 v135, 0x3d372713, v129
	v_mul_f32_e32 v136, 0x3d372713, v130
	v_mul_f32_e32 v137, 0x3d372713, v131
	v_mul_f32_e32 v134, v128, v134
	v_mul_f32_e32 v135, v129, v135
	v_mul_f32_e32 v136, v130, v136
	v_mul_f32_e32 v137, v131, v137
	v_fma_f32 v134, v128, v134, v128
	v_fma_f32 v135, v129, v135, v129
	v_fma_f32 v136, v130, v136, v130
	v_fma_f32 v137, v131, v137, v131
	v_mul_f32_e32 v134, 0x3fcc422a, v134
	v_mul_f32_e32 v135, 0x3fcc422a, v135
	v_mul_f32_e32 v136, 0x3fcc422a, v136
	v_mul_f32_e32 v137, 0x3fcc422a, v137
	v_mul_f32_e32 v134, 0xbfb8aa3b, v134
	v_mul_f32_e32 v135, 0xbfb8aa3b, v135
	v_mul_f32_e32 v136, 0xbfb8aa3b, v136
	v_mul_f32_e32 v137, 0xbfb8aa3b, v137
	v_exp_f32_e32 v134, v134
	v_exp_f32_e32 v135, v135
	v_exp_f32_e32 v136, v136
	v_exp_f32_e32 v137, v137
	v_add_f32_e32 v134, 1.0, v134
	v_add_f32_e32 v135, 1.0, v135
	v_add_f32_e32 v136, 1.0, v136
	v_add_f32_e32 v137, 1.0, v137
	v_rcp_f32_e32 v134, v134
	v_rcp_f32_e32 v135, v135
	v_rcp_f32_e32 v136, v136
	v_rcp_f32_e32 v137, v137
	s_nop 0
	v_pk_mul_f32 v[128:129], v[128:129], v[134:135]
	v_pk_mul_f32 v[130:131], v[130:131], v[136:137]
	v_fmac_f32_e32 v201, v128, v128
	v_fmac_f32_e32 v201, v129, v129
	v_fmac_f32_e32 v201, v130, v130
	v_fmac_f32_e32 v201, v131, v131
	v_cvt_pk_bf16_f32 v132, v128, v129
	v_cvt_pk_bf16_f32 v133, v130, v131
	ds_write_b16 v208, v132 offset:1312
	ds_write_b16_d16_hi v208, v132 offset:1392
	ds_write_b16 v208, v133 offset:1472
	ds_write_b16_d16_hi v208, v133 offset:1552
	s_waitcnt lgkmcnt(0)
	ds_read_b128 v[212:215], v209
	ds_read_b128 v[216:219], v209 offset:1280
	s_add_u32 s46, s44, s101
	s_addc_u32 s47, s45, 0
	s_add_u32 s46, s46, s100
	s_addc_u32 s47, s47, 0
	s_waitcnt lgkmcnt(0)
	global_store_dwordx4 v210, v[212:215], s[46:47]
	global_store_dwordx4 v211, v[216:219], s[46:47]
	v_pk_mul_f32 v[128:129], v[84:85], v[172:173] op_sel_hi:[1,0]
	v_pk_mul_f32 v[130:131], v[86:87], v[172:173] op_sel_hi:[1,0]
	v_mul_f32_e32 v134, 0x3d372713, v128
	v_mul_f32_e32 v135, 0x3d372713, v129
	v_mul_f32_e32 v136, 0x3d372713, v130
	v_mul_f32_e32 v137, 0x3d372713, v131
	v_mul_f32_e32 v134, v128, v134
	v_mul_f32_e32 v135, v129, v135
	v_mul_f32_e32 v136, v130, v136
	v_mul_f32_e32 v137, v131, v137
	v_fma_f32 v134, v128, v134, v128
	v_fma_f32 v135, v129, v135, v129
	v_fma_f32 v136, v130, v136, v130
	v_fma_f32 v137, v131, v137, v131
	v_mul_f32_e32 v134, 0x3fcc422a, v134
	v_mul_f32_e32 v135, 0x3fcc422a, v135
	v_mul_f32_e32 v136, 0x3fcc422a, v136
	v_mul_f32_e32 v137, 0x3fcc422a, v137
	v_mul_f32_e32 v134, 0xbfb8aa3b, v134
	v_mul_f32_e32 v135, 0xbfb8aa3b, v135
	v_mul_f32_e32 v136, 0xbfb8aa3b, v136
	v_mul_f32_e32 v137, 0xbfb8aa3b, v137
	v_exp_f32_e32 v134, v134
	v_exp_f32_e32 v135, v135
	v_exp_f32_e32 v136, v136
	v_exp_f32_e32 v137, v137
	v_add_f32_e32 v134, 1.0, v134
	v_add_f32_e32 v135, 1.0, v135
	v_add_f32_e32 v136, 1.0, v136
	v_add_f32_e32 v137, 1.0, v137
	v_rcp_f32_e32 v134, v134
	v_rcp_f32_e32 v135, v135
	v_rcp_f32_e32 v136, v136
	v_rcp_f32_e32 v137, v137
	s_nop 0
	v_pk_mul_f32 v[128:129], v[128:129], v[134:135]
	v_pk_mul_f32 v[130:131], v[130:131], v[136:137]
	v_fmac_f32_e32 v202, v128, v128
	v_fmac_f32_e32 v202, v129, v129
	v_fmac_f32_e32 v202, v130, v130
	v_fmac_f32_e32 v202, v131, v131
	v_cvt_pk_bf16_f32 v132, v128, v129
	v_cvt_pk_bf16_f32 v133, v130, v131
	ds_write_b16 v208, v132
	ds_write_b16_d16_hi v208, v132 offset:80
	ds_write_b16 v208, v133 offset:160
	ds_write_b16_d16_hi v208, v133 offset:240
	v_pk_mul_f32 v[128:129], v[80:81], v[172:173] op_sel_hi:[1,0]
	v_pk_mul_f32 v[130:131], v[82:83], v[172:173] op_sel_hi:[1,0]
	v_mul_f32_e32 v134, 0x3d372713, v128
	v_mul_f32_e32 v135, 0x3d372713, v129
	v_mul_f32_e32 v136, 0x3d372713, v130
	v_mul_f32_e32 v137, 0x3d372713, v131
	v_mul_f32_e32 v134, v128, v134
	v_mul_f32_e32 v135, v129, v135
	v_mul_f32_e32 v136, v130, v136
	v_mul_f32_e32 v137, v131, v137
	v_fma_f32 v134, v128, v134, v128
	v_fma_f32 v135, v129, v135, v129
	v_fma_f32 v136, v130, v136, v130
	v_fma_f32 v137, v131, v137, v131
	v_mul_f32_e32 v134, 0x3fcc422a, v134
	v_mul_f32_e32 v135, 0x3fcc422a, v135
	v_mul_f32_e32 v136, 0x3fcc422a, v136
	v_mul_f32_e32 v137, 0x3fcc422a, v137
	v_mul_f32_e32 v134, 0xbfb8aa3b, v134
	v_mul_f32_e32 v135, 0xbfb8aa3b, v135
	v_mul_f32_e32 v136, 0xbfb8aa3b, v136
	v_mul_f32_e32 v137, 0xbfb8aa3b, v137
	v_exp_f32_e32 v134, v134
	v_exp_f32_e32 v135, v135
	v_exp_f32_e32 v136, v136
	v_exp_f32_e32 v137, v137
	v_add_f32_e32 v134, 1.0, v134
	v_add_f32_e32 v135, 1.0, v135
	v_add_f32_e32 v136, 1.0, v136
	v_add_f32_e32 v137, 1.0, v137
	v_rcp_f32_e32 v134, v134
	v_rcp_f32_e32 v135, v135
	v_rcp_f32_e32 v136, v136
	v_rcp_f32_e32 v137, v137
	s_nop 0
	v_pk_mul_f32 v[128:129], v[128:129], v[134:135]
	v_pk_mul_f32 v[130:131], v[130:131], v[136:137]
	v_fmac_f32_e32 v202, v128, v128
	v_fmac_f32_e32 v202, v129, v129
	v_fmac_f32_e32 v202, v130, v130
	v_fmac_f32_e32 v202, v131, v131
	v_cvt_pk_bf16_f32 v132, v128, v129
	v_cvt_pk_bf16_f32 v133, v130, v131
	ds_write_b16 v208, v132 offset:1280
	ds_write_b16_d16_hi v208, v132 offset:1360
	ds_write_b16 v208, v133 offset:1440
	ds_write_b16_d16_hi v208, v133 offset:1520
	v_pk_mul_f32 v[128:129], v[68:69], v[168:169] op_sel_hi:[1,0]
	v_pk_mul_f32 v[130:131], v[70:71], v[168:169] op_sel_hi:[1,0]
	v_mul_f32_e32 v134, 0x3d372713, v128
	v_mul_f32_e32 v135, 0x3d372713, v129
	v_mul_f32_e32 v136, 0x3d372713, v130
	v_mul_f32_e32 v137, 0x3d372713, v131
	v_mul_f32_e32 v134, v128, v134
	v_mul_f32_e32 v135, v129, v135
	v_mul_f32_e32 v136, v130, v136
	v_mul_f32_e32 v137, v131, v137
	v_fma_f32 v134, v128, v134, v128
	v_fma_f32 v135, v129, v135, v129
	v_fma_f32 v136, v130, v136, v130
	v_fma_f32 v137, v131, v137, v131
	v_mul_f32_e32 v134, 0x3fcc422a, v134
	v_mul_f32_e32 v135, 0x3fcc422a, v135
	v_mul_f32_e32 v136, 0x3fcc422a, v136
	v_mul_f32_e32 v137, 0x3fcc422a, v137
	v_mul_f32_e32 v134, 0xbfb8aa3b, v134
	v_mul_f32_e32 v135, 0xbfb8aa3b, v135
	v_mul_f32_e32 v136, 0xbfb8aa3b, v136
	v_mul_f32_e32 v137, 0xbfb8aa3b, v137
	v_exp_f32_e32 v134, v134
	v_exp_f32_e32 v135, v135
	v_exp_f32_e32 v136, v136
	v_exp_f32_e32 v137, v137
	v_add_f32_e32 v134, 1.0, v134
	v_add_f32_e32 v135, 1.0, v135
	v_add_f32_e32 v136, 1.0, v136
	v_add_f32_e32 v137, 1.0, v137
	v_rcp_f32_e32 v134, v134
	v_rcp_f32_e32 v135, v135
	v_rcp_f32_e32 v136, v136
	v_rcp_f32_e32 v137, v137
	s_nop 0
	v_pk_mul_f32 v[128:129], v[128:129], v[134:135]
	v_pk_mul_f32 v[130:131], v[130:131], v[136:137]
	v_fmac_f32_e32 v203, v128, v128
	v_fmac_f32_e32 v203, v129, v129
	v_fmac_f32_e32 v203, v130, v130
	v_fmac_f32_e32 v203, v131, v131
	v_cvt_pk_bf16_f32 v132, v128, v129
	v_cvt_pk_bf16_f32 v133, v130, v131
	ds_write_b16 v208, v132 offset:32
	ds_write_b16_d16_hi v208, v132 offset:112
	ds_write_b16 v208, v133 offset:192
	ds_write_b16_d16_hi v208, v133 offset:272
	v_pk_mul_f32 v[128:129], v[64:65], v[168:169] op_sel_hi:[1,0]
	v_pk_mul_f32 v[130:131], v[66:67], v[168:169] op_sel_hi:[1,0]
	v_mul_f32_e32 v134, 0x3d372713, v128
	v_mul_f32_e32 v135, 0x3d372713, v129
	v_mul_f32_e32 v136, 0x3d372713, v130
	v_mul_f32_e32 v137, 0x3d372713, v131
	v_mul_f32_e32 v134, v128, v134
	v_mul_f32_e32 v135, v129, v135
	v_mul_f32_e32 v136, v130, v136
	v_mul_f32_e32 v137, v131, v137
	v_fma_f32 v134, v128, v134, v128
	v_fma_f32 v135, v129, v135, v129
	v_fma_f32 v136, v130, v136, v130
	v_fma_f32 v137, v131, v137, v131
	v_mul_f32_e32 v134, 0x3fcc422a, v134
	v_mul_f32_e32 v135, 0x3fcc422a, v135
	v_mul_f32_e32 v136, 0x3fcc422a, v136
	v_mul_f32_e32 v137, 0x3fcc422a, v137
	v_mul_f32_e32 v134, 0xbfb8aa3b, v134
	v_mul_f32_e32 v135, 0xbfb8aa3b, v135
	v_mul_f32_e32 v136, 0xbfb8aa3b, v136
	v_mul_f32_e32 v137, 0xbfb8aa3b, v137
	v_exp_f32_e32 v134, v134
	v_exp_f32_e32 v135, v135
	v_exp_f32_e32 v136, v136
	v_exp_f32_e32 v137, v137
	v_add_f32_e32 v134, 1.0, v134
	v_add_f32_e32 v135, 1.0, v135
	v_add_f32_e32 v136, 1.0, v136
	v_add_f32_e32 v137, 1.0, v137
	v_rcp_f32_e32 v134, v134
	v_rcp_f32_e32 v135, v135
	v_rcp_f32_e32 v136, v136
	v_rcp_f32_e32 v137, v137
	s_nop 0
	v_pk_mul_f32 v[128:129], v[128:129], v[134:135]
	v_pk_mul_f32 v[130:131], v[130:131], v[136:137]
	v_fmac_f32_e32 v203, v128, v128
	v_fmac_f32_e32 v203, v129, v129
	v_fmac_f32_e32 v203, v130, v130
	v_fmac_f32_e32 v203, v131, v131
	v_cvt_pk_bf16_f32 v132, v128, v129
	v_cvt_pk_bf16_f32 v133, v130, v131
	ds_write_b16 v208, v132 offset:1312
	ds_write_b16_d16_hi v208, v132 offset:1392
	ds_write_b16 v208, v133 offset:1472
	ds_write_b16_d16_hi v208, v133 offset:1552
	s_waitcnt lgkmcnt(0)
	ds_read_b128 v[212:215], v209
	ds_read_b128 v[216:219], v209 offset:1280
	s_add_u32 s46, s44, s101
	s_addc_u32 s47, s45, 0
	s_add_u32 s46, s46, s100
	s_addc_u32 s47, s47, 0
	s_waitcnt lgkmcnt(0)
	global_store_dwordx4 v210, v[212:215], s[46:47] offset:64
	global_store_dwordx4 v211, v[216:219], s[46:47] offset:64
	v_pk_mul_f32 v[128:129], v[60:61], v[164:165] op_sel_hi:[1,0]
	v_pk_mul_f32 v[130:131], v[62:63], v[164:165] op_sel_hi:[1,0]
	v_mul_f32_e32 v134, 0x3d372713, v128
	v_mul_f32_e32 v135, 0x3d372713, v129
	v_mul_f32_e32 v136, 0x3d372713, v130
	v_mul_f32_e32 v137, 0x3d372713, v131
	v_mul_f32_e32 v134, v128, v134
	v_mul_f32_e32 v135, v129, v135
	v_mul_f32_e32 v136, v130, v136
	v_mul_f32_e32 v137, v131, v137
	v_fma_f32 v134, v128, v134, v128
	v_fma_f32 v135, v129, v135, v129
	v_fma_f32 v136, v130, v136, v130
	v_fma_f32 v137, v131, v137, v131
	v_mul_f32_e32 v134, 0x3fcc422a, v134
	v_mul_f32_e32 v135, 0x3fcc422a, v135
	v_mul_f32_e32 v136, 0x3fcc422a, v136
	v_mul_f32_e32 v137, 0x3fcc422a, v137
	v_mul_f32_e32 v134, 0xbfb8aa3b, v134
	v_mul_f32_e32 v135, 0xbfb8aa3b, v135
	v_mul_f32_e32 v136, 0xbfb8aa3b, v136
	v_mul_f32_e32 v137, 0xbfb8aa3b, v137
	v_exp_f32_e32 v134, v134
	v_exp_f32_e32 v135, v135
	v_exp_f32_e32 v136, v136
	v_exp_f32_e32 v137, v137
	v_add_f32_e32 v134, 1.0, v134
	v_add_f32_e32 v135, 1.0, v135
	v_add_f32_e32 v136, 1.0, v136
	v_add_f32_e32 v137, 1.0, v137
	v_rcp_f32_e32 v134, v134
	v_rcp_f32_e32 v135, v135
	v_rcp_f32_e32 v136, v136
	v_rcp_f32_e32 v137, v137
	s_nop 0
	v_pk_mul_f32 v[128:129], v[128:129], v[134:135]
	v_pk_mul_f32 v[130:131], v[130:131], v[136:137]
	v_mul_f32_e32 v204, v128, v128
	v_fmac_f32_e32 v204, v129, v129
	v_fmac_f32_e32 v204, v130, v130
	v_fmac_f32_e32 v204, v131, v131
	v_cvt_pk_bf16_f32 v132, v128, v129
	v_cvt_pk_bf16_f32 v133, v130, v131
	ds_write_b16 v208, v132
	ds_write_b16_d16_hi v208, v132 offset:80
	ds_write_b16 v208, v133 offset:160
	ds_write_b16_d16_hi v208, v133 offset:240
	v_pk_mul_f32 v[128:129], v[56:57], v[164:165] op_sel_hi:[1,0]
	v_pk_mul_f32 v[130:131], v[58:59], v[164:165] op_sel_hi:[1,0]
	v_mul_f32_e32 v134, 0x3d372713, v128
	v_mul_f32_e32 v135, 0x3d372713, v129
	v_mul_f32_e32 v136, 0x3d372713, v130
	v_mul_f32_e32 v137, 0x3d372713, v131
	v_mul_f32_e32 v134, v128, v134
	v_mul_f32_e32 v135, v129, v135
	v_mul_f32_e32 v136, v130, v136
	v_mul_f32_e32 v137, v131, v137
	v_fma_f32 v134, v128, v134, v128
	v_fma_f32 v135, v129, v135, v129
	v_fma_f32 v136, v130, v136, v130
	v_fma_f32 v137, v131, v137, v131
	v_mul_f32_e32 v134, 0x3fcc422a, v134
	v_mul_f32_e32 v135, 0x3fcc422a, v135
	v_mul_f32_e32 v136, 0x3fcc422a, v136
	v_mul_f32_e32 v137, 0x3fcc422a, v137
	v_mul_f32_e32 v134, 0xbfb8aa3b, v134
	v_mul_f32_e32 v135, 0xbfb8aa3b, v135
	v_mul_f32_e32 v136, 0xbfb8aa3b, v136
	v_mul_f32_e32 v137, 0xbfb8aa3b, v137
	v_exp_f32_e32 v134, v134
	v_exp_f32_e32 v135, v135
	v_exp_f32_e32 v136, v136
	v_exp_f32_e32 v137, v137
	v_add_f32_e32 v134, 1.0, v134
	v_add_f32_e32 v135, 1.0, v135
	v_add_f32_e32 v136, 1.0, v136
	v_add_f32_e32 v137, 1.0, v137
	v_rcp_f32_e32 v134, v134
	v_rcp_f32_e32 v135, v135
	v_rcp_f32_e32 v136, v136
	v_rcp_f32_e32 v137, v137
	s_nop 0
	v_pk_mul_f32 v[128:129], v[128:129], v[134:135]
	v_pk_mul_f32 v[130:131], v[130:131], v[136:137]
	v_fmac_f32_e32 v204, v128, v128
	v_fmac_f32_e32 v204, v129, v129
	v_fmac_f32_e32 v204, v130, v130
	v_fmac_f32_e32 v204, v131, v131
	v_cvt_pk_bf16_f32 v132, v128, v129
	v_cvt_pk_bf16_f32 v133, v130, v131
	ds_write_b16 v208, v132 offset:1280
	ds_write_b16_d16_hi v208, v132 offset:1360
	ds_write_b16 v208, v133 offset:1440
	ds_write_b16_d16_hi v208, v133 offset:1520
	v_pk_mul_f32 v[128:129], v[44:45], v[160:161] op_sel_hi:[1,0]
	v_pk_mul_f32 v[130:131], v[46:47], v[160:161] op_sel_hi:[1,0]
	v_mul_f32_e32 v134, 0x3d372713, v128
	v_mul_f32_e32 v135, 0x3d372713, v129
	v_mul_f32_e32 v136, 0x3d372713, v130
	v_mul_f32_e32 v137, 0x3d372713, v131
	v_mul_f32_e32 v134, v128, v134
	v_mul_f32_e32 v135, v129, v135
	v_mul_f32_e32 v136, v130, v136
	v_mul_f32_e32 v137, v131, v137
	v_fma_f32 v134, v128, v134, v128
	v_fma_f32 v135, v129, v135, v129
	v_fma_f32 v136, v130, v136, v130
	v_fma_f32 v137, v131, v137, v131
	v_mul_f32_e32 v134, 0x3fcc422a, v134
	v_mul_f32_e32 v135, 0x3fcc422a, v135
	v_mul_f32_e32 v136, 0x3fcc422a, v136
	v_mul_f32_e32 v137, 0x3fcc422a, v137
	v_mul_f32_e32 v134, 0xbfb8aa3b, v134
	v_mul_f32_e32 v135, 0xbfb8aa3b, v135
	v_mul_f32_e32 v136, 0xbfb8aa3b, v136
	v_mul_f32_e32 v137, 0xbfb8aa3b, v137
	v_exp_f32_e32 v134, v134
	v_exp_f32_e32 v135, v135
	v_exp_f32_e32 v136, v136
	v_exp_f32_e32 v137, v137
	v_add_f32_e32 v134, 1.0, v134
	v_add_f32_e32 v135, 1.0, v135
	v_add_f32_e32 v136, 1.0, v136
	v_add_f32_e32 v137, 1.0, v137
	v_rcp_f32_e32 v134, v134
	v_rcp_f32_e32 v135, v135
	v_rcp_f32_e32 v136, v136
	v_rcp_f32_e32 v137, v137
	s_nop 0
	v_pk_mul_f32 v[128:129], v[128:129], v[134:135]
	v_pk_mul_f32 v[130:131], v[130:131], v[136:137]
	v_mul_f32_e32 v205, v128, v128
	v_fmac_f32_e32 v205, v129, v129
	v_fmac_f32_e32 v205, v130, v130
	v_fmac_f32_e32 v205, v131, v131
	v_cvt_pk_bf16_f32 v132, v128, v129
	v_cvt_pk_bf16_f32 v133, v130, v131
	ds_write_b16 v208, v132 offset:32
	ds_write_b16_d16_hi v208, v132 offset:112
	ds_write_b16 v208, v133 offset:192
	ds_write_b16_d16_hi v208, v133 offset:272
	v_pk_mul_f32 v[128:129], v[40:41], v[160:161] op_sel_hi:[1,0]
	v_pk_mul_f32 v[130:131], v[42:43], v[160:161] op_sel_hi:[1,0]
	v_mul_f32_e32 v134, 0x3d372713, v128
	v_mul_f32_e32 v135, 0x3d372713, v129
	v_mul_f32_e32 v136, 0x3d372713, v130
	v_mul_f32_e32 v137, 0x3d372713, v131
	v_mul_f32_e32 v134, v128, v134
	v_mul_f32_e32 v135, v129, v135
	v_mul_f32_e32 v136, v130, v136
	v_mul_f32_e32 v137, v131, v137
	v_fma_f32 v134, v128, v134, v128
	v_fma_f32 v135, v129, v135, v129
	v_fma_f32 v136, v130, v136, v130
	v_fma_f32 v137, v131, v137, v131
	v_mul_f32_e32 v134, 0x3fcc422a, v134
	v_mul_f32_e32 v135, 0x3fcc422a, v135
	v_mul_f32_e32 v136, 0x3fcc422a, v136
	v_mul_f32_e32 v137, 0x3fcc422a, v137
	v_mul_f32_e32 v134, 0xbfb8aa3b, v134
	v_mul_f32_e32 v135, 0xbfb8aa3b, v135
	v_mul_f32_e32 v136, 0xbfb8aa3b, v136
	v_mul_f32_e32 v137, 0xbfb8aa3b, v137
	v_exp_f32_e32 v134, v134
	v_exp_f32_e32 v135, v135
	v_exp_f32_e32 v136, v136
	v_exp_f32_e32 v137, v137
	v_add_f32_e32 v134, 1.0, v134
	v_add_f32_e32 v135, 1.0, v135
	v_add_f32_e32 v136, 1.0, v136
	v_add_f32_e32 v137, 1.0, v137
	v_rcp_f32_e32 v134, v134
	v_rcp_f32_e32 v135, v135
	v_rcp_f32_e32 v136, v136
	v_rcp_f32_e32 v137, v137
	s_nop 0
	v_pk_mul_f32 v[128:129], v[128:129], v[134:135]
	v_pk_mul_f32 v[130:131], v[130:131], v[136:137]
	v_fmac_f32_e32 v205, v128, v128
	v_fmac_f32_e32 v205, v129, v129
	v_fmac_f32_e32 v205, v130, v130
	v_fmac_f32_e32 v205, v131, v131
	v_cvt_pk_bf16_f32 v132, v128, v129
	v_cvt_pk_bf16_f32 v133, v130, v131
	ds_write_b16 v208, v132 offset:1312
	ds_write_b16_d16_hi v208, v132 offset:1392
	ds_write_b16 v208, v133 offset:1472
	ds_write_b16_d16_hi v208, v133 offset:1552
	s_waitcnt lgkmcnt(0)
	ds_read_b128 v[212:215], v209
	ds_read_b128 v[216:219], v209 offset:1280
	s_add_u32 s46, s44, s38
	s_addc_u32 s47, s45, 0
	s_waitcnt lgkmcnt(0)
	global_store_dwordx4 v210, v[212:215], s[46:47]
	global_store_dwordx4 v211, v[216:219], s[46:47]
	v_pk_mul_f32 v[128:129], v[28:29], v[156:157] op_sel_hi:[1,0]
	v_pk_mul_f32 v[130:131], v[30:31], v[156:157] op_sel_hi:[1,0]
	v_mul_f32_e32 v134, 0x3d372713, v128
	v_mul_f32_e32 v135, 0x3d372713, v129
	v_mul_f32_e32 v136, 0x3d372713, v130
	v_mul_f32_e32 v137, 0x3d372713, v131
	v_mul_f32_e32 v134, v128, v134
	v_mul_f32_e32 v135, v129, v135
	v_mul_f32_e32 v136, v130, v136
	v_mul_f32_e32 v137, v131, v137
	v_fma_f32 v134, v128, v134, v128
	v_fma_f32 v135, v129, v135, v129
	v_fma_f32 v136, v130, v136, v130
	v_fma_f32 v137, v131, v137, v131
	v_mul_f32_e32 v134, 0x3fcc422a, v134
	v_mul_f32_e32 v135, 0x3fcc422a, v135
	v_mul_f32_e32 v136, 0x3fcc422a, v136
	v_mul_f32_e32 v137, 0x3fcc422a, v137
	v_mul_f32_e32 v134, 0xbfb8aa3b, v134
	v_mul_f32_e32 v135, 0xbfb8aa3b, v135
	v_mul_f32_e32 v136, 0xbfb8aa3b, v136
	v_mul_f32_e32 v137, 0xbfb8aa3b, v137
	v_exp_f32_e32 v134, v134
	v_exp_f32_e32 v135, v135
	v_exp_f32_e32 v136, v136
	v_exp_f32_e32 v137, v137
	v_add_f32_e32 v134, 1.0, v134
	v_add_f32_e32 v135, 1.0, v135
	v_add_f32_e32 v136, 1.0, v136
	v_add_f32_e32 v137, 1.0, v137
	v_rcp_f32_e32 v134, v134
	v_rcp_f32_e32 v135, v135
	v_rcp_f32_e32 v136, v136
	v_rcp_f32_e32 v137, v137
	s_nop 0
	v_pk_mul_f32 v[128:129], v[128:129], v[134:135]
	v_pk_mul_f32 v[130:131], v[130:131], v[136:137]
	v_mul_f32_e32 v206, v128, v128
	v_fmac_f32_e32 v206, v129, v129
	v_fmac_f32_e32 v206, v130, v130
	v_fmac_f32_e32 v206, v131, v131
	v_cvt_pk_bf16_f32 v132, v128, v129
	v_cvt_pk_bf16_f32 v133, v130, v131
	ds_write_b16 v208, v132
	ds_write_b16_d16_hi v208, v132 offset:80
	ds_write_b16 v208, v133 offset:160
	ds_write_b16_d16_hi v208, v133 offset:240
	v_pk_mul_f32 v[128:129], v[24:25], v[156:157] op_sel_hi:[1,0]
	v_pk_mul_f32 v[130:131], v[26:27], v[156:157] op_sel_hi:[1,0]
	v_mul_f32_e32 v134, 0x3d372713, v128
	v_mul_f32_e32 v135, 0x3d372713, v129
	v_mul_f32_e32 v136, 0x3d372713, v130
	v_mul_f32_e32 v137, 0x3d372713, v131
	v_mul_f32_e32 v134, v128, v134
	v_mul_f32_e32 v135, v129, v135
	v_mul_f32_e32 v136, v130, v136
	v_mul_f32_e32 v137, v131, v137
	v_fma_f32 v134, v128, v134, v128
	v_fma_f32 v135, v129, v135, v129
	v_fma_f32 v136, v130, v136, v130
	v_fma_f32 v137, v131, v137, v131
	v_mul_f32_e32 v134, 0x3fcc422a, v134
	v_mul_f32_e32 v135, 0x3fcc422a, v135
	v_mul_f32_e32 v136, 0x3fcc422a, v136
	v_mul_f32_e32 v137, 0x3fcc422a, v137
	v_mul_f32_e32 v134, 0xbfb8aa3b, v134
	v_mul_f32_e32 v135, 0xbfb8aa3b, v135
	v_mul_f32_e32 v136, 0xbfb8aa3b, v136
	v_mul_f32_e32 v137, 0xbfb8aa3b, v137
	v_exp_f32_e32 v134, v134
	v_exp_f32_e32 v135, v135
	v_exp_f32_e32 v136, v136
	v_exp_f32_e32 v137, v137
	v_add_f32_e32 v134, 1.0, v134
	v_add_f32_e32 v135, 1.0, v135
	v_add_f32_e32 v136, 1.0, v136
	v_add_f32_e32 v137, 1.0, v137
	v_rcp_f32_e32 v134, v134
	v_rcp_f32_e32 v135, v135
	v_rcp_f32_e32 v136, v136
	v_rcp_f32_e32 v137, v137
	s_nop 0
	v_pk_mul_f32 v[128:129], v[128:129], v[134:135]
	v_pk_mul_f32 v[130:131], v[130:131], v[136:137]
	v_fmac_f32_e32 v206, v128, v128
	v_fmac_f32_e32 v206, v129, v129
	v_fmac_f32_e32 v206, v130, v130
	v_fmac_f32_e32 v206, v131, v131
	v_cvt_pk_bf16_f32 v132, v128, v129
	v_cvt_pk_bf16_f32 v133, v130, v131
	ds_write_b16 v208, v132 offset:1280
	ds_write_b16_d16_hi v208, v132 offset:1360
	ds_write_b16 v208, v133 offset:1440
	ds_write_b16_d16_hi v208, v133 offset:1520
	v_pk_mul_f32 v[128:129], v[12:13], v[152:153] op_sel_hi:[1,0]
	v_pk_mul_f32 v[130:131], v[14:15], v[152:153] op_sel_hi:[1,0]
	v_mul_f32_e32 v134, 0x3d372713, v128
	v_mul_f32_e32 v135, 0x3d372713, v129
	v_mul_f32_e32 v136, 0x3d372713, v130
	v_mul_f32_e32 v137, 0x3d372713, v131
	v_mul_f32_e32 v134, v128, v134
	v_mul_f32_e32 v135, v129, v135
	v_mul_f32_e32 v136, v130, v136
	v_mul_f32_e32 v137, v131, v137
	v_fma_f32 v134, v128, v134, v128
	v_fma_f32 v135, v129, v135, v129
	v_fma_f32 v136, v130, v136, v130
	v_fma_f32 v137, v131, v137, v131
	v_mul_f32_e32 v134, 0x3fcc422a, v134
	v_mul_f32_e32 v135, 0x3fcc422a, v135
	v_mul_f32_e32 v136, 0x3fcc422a, v136
	v_mul_f32_e32 v137, 0x3fcc422a, v137
	v_mul_f32_e32 v134, 0xbfb8aa3b, v134
	v_mul_f32_e32 v135, 0xbfb8aa3b, v135
	v_mul_f32_e32 v136, 0xbfb8aa3b, v136
	v_mul_f32_e32 v137, 0xbfb8aa3b, v137
	v_exp_f32_e32 v134, v134
	v_exp_f32_e32 v135, v135
	v_exp_f32_e32 v136, v136
	v_exp_f32_e32 v137, v137
	v_add_f32_e32 v134, 1.0, v134
	v_add_f32_e32 v135, 1.0, v135
	v_add_f32_e32 v136, 1.0, v136
	v_add_f32_e32 v137, 1.0, v137
	v_rcp_f32_e32 v134, v134
	v_rcp_f32_e32 v135, v135
	v_rcp_f32_e32 v136, v136
	v_rcp_f32_e32 v137, v137
	s_nop 0
	v_pk_mul_f32 v[128:129], v[128:129], v[134:135]
	v_pk_mul_f32 v[130:131], v[130:131], v[136:137]
	v_mul_f32_e32 v207, v128, v128
	v_fmac_f32_e32 v207, v129, v129
	v_fmac_f32_e32 v207, v130, v130
	v_fmac_f32_e32 v207, v131, v131
	v_cvt_pk_bf16_f32 v132, v128, v129
	v_cvt_pk_bf16_f32 v133, v130, v131
	ds_write_b16 v208, v132 offset:32
	ds_write_b16_d16_hi v208, v132 offset:112
	ds_write_b16 v208, v133 offset:192
	ds_write_b16_d16_hi v208, v133 offset:272
	v_pk_mul_f32 v[128:129], v[8:9], v[152:153] op_sel_hi:[1,0]
	v_pk_mul_f32 v[130:131], v[10:11], v[152:153] op_sel_hi:[1,0]
	v_mul_f32_e32 v134, 0x3d372713, v128
	v_mul_f32_e32 v135, 0x3d372713, v129
	v_mul_f32_e32 v136, 0x3d372713, v130
	v_mul_f32_e32 v137, 0x3d372713, v131
	v_mul_f32_e32 v134, v128, v134
	v_mul_f32_e32 v135, v129, v135
	v_mul_f32_e32 v136, v130, v136
	v_mul_f32_e32 v137, v131, v137
	v_fma_f32 v134, v128, v134, v128
	v_fma_f32 v135, v129, v135, v129
	v_fma_f32 v136, v130, v136, v130
	v_fma_f32 v137, v131, v137, v131
	v_mul_f32_e32 v134, 0x3fcc422a, v134
	v_mul_f32_e32 v135, 0x3fcc422a, v135
	v_mul_f32_e32 v136, 0x3fcc422a, v136
	v_mul_f32_e32 v137, 0x3fcc422a, v137
	v_mul_f32_e32 v134, 0xbfb8aa3b, v134
	v_mul_f32_e32 v135, 0xbfb8aa3b, v135
	v_mul_f32_e32 v136, 0xbfb8aa3b, v136
	v_mul_f32_e32 v137, 0xbfb8aa3b, v137
	v_exp_f32_e32 v134, v134
	v_exp_f32_e32 v135, v135
	v_exp_f32_e32 v136, v136
	v_exp_f32_e32 v137, v137
	v_add_f32_e32 v134, 1.0, v134
	v_add_f32_e32 v135, 1.0, v135
	v_add_f32_e32 v136, 1.0, v136
	v_add_f32_e32 v137, 1.0, v137
	v_rcp_f32_e32 v134, v134
	v_rcp_f32_e32 v135, v135
	v_rcp_f32_e32 v136, v136
	v_rcp_f32_e32 v137, v137
	s_nop 0
	v_pk_mul_f32 v[128:129], v[128:129], v[134:135]
	v_pk_mul_f32 v[130:131], v[130:131], v[136:137]
	v_fmac_f32_e32 v207, v128, v128
	v_fmac_f32_e32 v207, v129, v129
	v_fmac_f32_e32 v207, v130, v130
	v_fmac_f32_e32 v207, v131, v131
	v_cvt_pk_bf16_f32 v132, v128, v129
	v_cvt_pk_bf16_f32 v133, v130, v131
	ds_write_b16 v208, v132 offset:1312
	ds_write_b16_d16_hi v208, v132 offset:1392
	ds_write_b16 v208, v133 offset:1472
	ds_write_b16_d16_hi v208, v133 offset:1552
	s_waitcnt lgkmcnt(0)
	ds_read_b128 v[212:215], v209
	ds_read_b128 v[216:219], v209 offset:1280
	s_add_u32 s46, s44, s38
	s_addc_u32 s47, s45, 0
	s_waitcnt lgkmcnt(0)
	global_store_dwordx4 v210, v[212:215], s[46:47] offset:64
	global_store_dwordx4 v211, v[216:219], s[46:47] offset:64
	v_pk_mul_f32 v[128:129], v[52:53], v[164:165] op_sel_hi:[1,0]
	v_pk_mul_f32 v[130:131], v[54:55], v[164:165] op_sel_hi:[1,0]
	v_mul_f32_e32 v134, 0x3d372713, v128
	v_mul_f32_e32 v135, 0x3d372713, v129
	v_mul_f32_e32 v136, 0x3d372713, v130
	v_mul_f32_e32 v137, 0x3d372713, v131
	v_mul_f32_e32 v134, v128, v134
	v_mul_f32_e32 v135, v129, v135
	v_mul_f32_e32 v136, v130, v136
	v_mul_f32_e32 v137, v131, v137
	v_fma_f32 v134, v128, v134, v128
	v_fma_f32 v135, v129, v135, v129
	v_fma_f32 v136, v130, v136, v130
	v_fma_f32 v137, v131, v137, v131
	v_mul_f32_e32 v134, 0x3fcc422a, v134
	v_mul_f32_e32 v135, 0x3fcc422a, v135
	v_mul_f32_e32 v136, 0x3fcc422a, v136
	v_mul_f32_e32 v137, 0x3fcc422a, v137
	v_mul_f32_e32 v134, 0xbfb8aa3b, v134
	v_mul_f32_e32 v135, 0xbfb8aa3b, v135
	v_mul_f32_e32 v136, 0xbfb8aa3b, v136
	v_mul_f32_e32 v137, 0xbfb8aa3b, v137
	v_exp_f32_e32 v134, v134
	v_exp_f32_e32 v135, v135
	v_exp_f32_e32 v136, v136
	v_exp_f32_e32 v137, v137
	v_add_f32_e32 v134, 1.0, v134
	v_add_f32_e32 v135, 1.0, v135
	v_add_f32_e32 v136, 1.0, v136
	v_add_f32_e32 v137, 1.0, v137
	v_rcp_f32_e32 v134, v134
	v_rcp_f32_e32 v135, v135
	v_rcp_f32_e32 v136, v136
	v_rcp_f32_e32 v137, v137
	s_nop 0
	v_pk_mul_f32 v[128:129], v[128:129], v[134:135]
	v_pk_mul_f32 v[130:131], v[130:131], v[136:137]
	v_fmac_f32_e32 v204, v128, v128
	v_fmac_f32_e32 v204, v129, v129
	v_fmac_f32_e32 v204, v130, v130
	v_fmac_f32_e32 v204, v131, v131
	v_cvt_pk_bf16_f32 v132, v128, v129
	v_cvt_pk_bf16_f32 v133, v130, v131
	ds_write_b16 v208, v132
	ds_write_b16_d16_hi v208, v132 offset:80
	ds_write_b16 v208, v133 offset:160
	ds_write_b16_d16_hi v208, v133 offset:240
	v_pk_mul_f32 v[128:129], v[48:49], v[164:165] op_sel_hi:[1,0]
	v_pk_mul_f32 v[130:131], v[50:51], v[164:165] op_sel_hi:[1,0]
	v_mul_f32_e32 v134, 0x3d372713, v128
	v_mul_f32_e32 v135, 0x3d372713, v129
	v_mul_f32_e32 v136, 0x3d372713, v130
	v_mul_f32_e32 v137, 0x3d372713, v131
	v_mul_f32_e32 v134, v128, v134
	v_mul_f32_e32 v135, v129, v135
	v_mul_f32_e32 v136, v130, v136
	v_mul_f32_e32 v137, v131, v137
	v_fma_f32 v134, v128, v134, v128
	v_fma_f32 v135, v129, v135, v129
	v_fma_f32 v136, v130, v136, v130
	v_fma_f32 v137, v131, v137, v131
	v_mul_f32_e32 v134, 0x3fcc422a, v134
	v_mul_f32_e32 v135, 0x3fcc422a, v135
	v_mul_f32_e32 v136, 0x3fcc422a, v136
	v_mul_f32_e32 v137, 0x3fcc422a, v137
	v_mul_f32_e32 v134, 0xbfb8aa3b, v134
	v_mul_f32_e32 v135, 0xbfb8aa3b, v135
	v_mul_f32_e32 v136, 0xbfb8aa3b, v136
	v_mul_f32_e32 v137, 0xbfb8aa3b, v137
	v_exp_f32_e32 v134, v134
	v_exp_f32_e32 v135, v135
	v_exp_f32_e32 v136, v136
	v_exp_f32_e32 v137, v137
	v_add_f32_e32 v134, 1.0, v134
	v_add_f32_e32 v135, 1.0, v135
	v_add_f32_e32 v136, 1.0, v136
	v_add_f32_e32 v137, 1.0, v137
	v_rcp_f32_e32 v134, v134
	v_rcp_f32_e32 v135, v135
	v_rcp_f32_e32 v136, v136
	v_rcp_f32_e32 v137, v137
	s_nop 0
	v_pk_mul_f32 v[128:129], v[128:129], v[134:135]
	v_pk_mul_f32 v[130:131], v[130:131], v[136:137]
	v_fmac_f32_e32 v204, v128, v128
	v_fmac_f32_e32 v204, v129, v129
	v_fmac_f32_e32 v204, v130, v130
	v_fmac_f32_e32 v204, v131, v131
	v_cvt_pk_bf16_f32 v132, v128, v129
	v_cvt_pk_bf16_f32 v133, v130, v131
	ds_write_b16 v208, v132 offset:1280
	ds_write_b16_d16_hi v208, v132 offset:1360
	ds_write_b16 v208, v133 offset:1440
	ds_write_b16_d16_hi v208, v133 offset:1520
	v_pk_mul_f32 v[128:129], v[36:37], v[160:161] op_sel_hi:[1,0]
	v_pk_mul_f32 v[130:131], v[38:39], v[160:161] op_sel_hi:[1,0]
	v_mul_f32_e32 v134, 0x3d372713, v128
	v_mul_f32_e32 v135, 0x3d372713, v129
	v_mul_f32_e32 v136, 0x3d372713, v130
	v_mul_f32_e32 v137, 0x3d372713, v131
	v_mul_f32_e32 v134, v128, v134
	v_mul_f32_e32 v135, v129, v135
	v_mul_f32_e32 v136, v130, v136
	v_mul_f32_e32 v137, v131, v137
	v_fma_f32 v134, v128, v134, v128
	v_fma_f32 v135, v129, v135, v129
	v_fma_f32 v136, v130, v136, v130
	v_fma_f32 v137, v131, v137, v131
	v_mul_f32_e32 v134, 0x3fcc422a, v134
	v_mul_f32_e32 v135, 0x3fcc422a, v135
	v_mul_f32_e32 v136, 0x3fcc422a, v136
	v_mul_f32_e32 v137, 0x3fcc422a, v137
	v_mul_f32_e32 v134, 0xbfb8aa3b, v134
	v_mul_f32_e32 v135, 0xbfb8aa3b, v135
	v_mul_f32_e32 v136, 0xbfb8aa3b, v136
	v_mul_f32_e32 v137, 0xbfb8aa3b, v137
	v_exp_f32_e32 v134, v134
	v_exp_f32_e32 v135, v135
	v_exp_f32_e32 v136, v136
	v_exp_f32_e32 v137, v137
	v_add_f32_e32 v134, 1.0, v134
	v_add_f32_e32 v135, 1.0, v135
	v_add_f32_e32 v136, 1.0, v136
	v_add_f32_e32 v137, 1.0, v137
	v_rcp_f32_e32 v134, v134
	v_rcp_f32_e32 v135, v135
	v_rcp_f32_e32 v136, v136
	v_rcp_f32_e32 v137, v137
	s_nop 0
	v_pk_mul_f32 v[128:129], v[128:129], v[134:135]
	v_pk_mul_f32 v[130:131], v[130:131], v[136:137]
	v_fmac_f32_e32 v205, v128, v128
	v_fmac_f32_e32 v205, v129, v129
	v_fmac_f32_e32 v205, v130, v130
	v_fmac_f32_e32 v205, v131, v131
	v_cvt_pk_bf16_f32 v132, v128, v129
	v_cvt_pk_bf16_f32 v133, v130, v131
	ds_write_b16 v208, v132 offset:32
	ds_write_b16_d16_hi v208, v132 offset:112
	ds_write_b16 v208, v133 offset:192
	ds_write_b16_d16_hi v208, v133 offset:272
	v_pk_mul_f32 v[128:129], v[32:33], v[160:161] op_sel_hi:[1,0]
	v_pk_mul_f32 v[130:131], v[34:35], v[160:161] op_sel_hi:[1,0]
	v_mul_f32_e32 v134, 0x3d372713, v128
	v_mul_f32_e32 v135, 0x3d372713, v129
	v_mul_f32_e32 v136, 0x3d372713, v130
	v_mul_f32_e32 v137, 0x3d372713, v131
	v_mul_f32_e32 v134, v128, v134
	v_mul_f32_e32 v135, v129, v135
	v_mul_f32_e32 v136, v130, v136
	v_mul_f32_e32 v137, v131, v137
	v_fma_f32 v134, v128, v134, v128
	v_fma_f32 v135, v129, v135, v129
	v_fma_f32 v136, v130, v136, v130
	v_fma_f32 v137, v131, v137, v131
	v_mul_f32_e32 v134, 0x3fcc422a, v134
	v_mul_f32_e32 v135, 0x3fcc422a, v135
	v_mul_f32_e32 v136, 0x3fcc422a, v136
	v_mul_f32_e32 v137, 0x3fcc422a, v137
	v_mul_f32_e32 v134, 0xbfb8aa3b, v134
	v_mul_f32_e32 v135, 0xbfb8aa3b, v135
	v_mul_f32_e32 v136, 0xbfb8aa3b, v136
	v_mul_f32_e32 v137, 0xbfb8aa3b, v137
	v_exp_f32_e32 v134, v134
	v_exp_f32_e32 v135, v135
	v_exp_f32_e32 v136, v136
	v_exp_f32_e32 v137, v137
	v_add_f32_e32 v134, 1.0, v134
	v_add_f32_e32 v135, 1.0, v135
	v_add_f32_e32 v136, 1.0, v136
	v_add_f32_e32 v137, 1.0, v137
	v_rcp_f32_e32 v134, v134
	v_rcp_f32_e32 v135, v135
	v_rcp_f32_e32 v136, v136
	v_rcp_f32_e32 v137, v137
	s_nop 0
	v_pk_mul_f32 v[128:129], v[128:129], v[134:135]
	v_pk_mul_f32 v[130:131], v[130:131], v[136:137]
	v_fmac_f32_e32 v205, v128, v128
	v_fmac_f32_e32 v205, v129, v129
	v_fmac_f32_e32 v205, v130, v130
	v_fmac_f32_e32 v205, v131, v131
	v_cvt_pk_bf16_f32 v132, v128, v129
	v_cvt_pk_bf16_f32 v133, v130, v131
	ds_write_b16 v208, v132 offset:1312
	ds_write_b16_d16_hi v208, v132 offset:1392
	ds_write_b16 v208, v133 offset:1472
	ds_write_b16_d16_hi v208, v133 offset:1552
	s_waitcnt lgkmcnt(0)
	ds_read_b128 v[212:215], v209
	ds_read_b128 v[216:219], v209 offset:1280
	s_add_u32 s46, s44, s38
	s_addc_u32 s47, s45, 0
	s_add_u32 s46, s46, s100
	s_addc_u32 s47, s47, 0
	s_waitcnt lgkmcnt(0)
	global_store_dwordx4 v210, v[212:215], s[46:47]
	global_store_dwordx4 v211, v[216:219], s[46:47]
	v_pk_mul_f32 v[128:129], v[20:21], v[156:157] op_sel_hi:[1,0]
	v_pk_mul_f32 v[130:131], v[22:23], v[156:157] op_sel_hi:[1,0]
	v_mul_f32_e32 v134, 0x3d372713, v128
	v_mul_f32_e32 v135, 0x3d372713, v129
	v_mul_f32_e32 v136, 0x3d372713, v130
	v_mul_f32_e32 v137, 0x3d372713, v131
	v_mul_f32_e32 v134, v128, v134
	v_mul_f32_e32 v135, v129, v135
	v_mul_f32_e32 v136, v130, v136
	v_mul_f32_e32 v137, v131, v137
	v_fma_f32 v134, v128, v134, v128
	v_fma_f32 v135, v129, v135, v129
	v_fma_f32 v136, v130, v136, v130
	v_fma_f32 v137, v131, v137, v131
	v_mul_f32_e32 v134, 0x3fcc422a, v134
	v_mul_f32_e32 v135, 0x3fcc422a, v135
	v_mul_f32_e32 v136, 0x3fcc422a, v136
	v_mul_f32_e32 v137, 0x3fcc422a, v137
	v_mul_f32_e32 v134, 0xbfb8aa3b, v134
	v_mul_f32_e32 v135, 0xbfb8aa3b, v135
	v_mul_f32_e32 v136, 0xbfb8aa3b, v136
	v_mul_f32_e32 v137, 0xbfb8aa3b, v137
	v_exp_f32_e32 v134, v134
	v_exp_f32_e32 v135, v135
	v_exp_f32_e32 v136, v136
	v_exp_f32_e32 v137, v137
	v_add_f32_e32 v134, 1.0, v134
	v_add_f32_e32 v135, 1.0, v135
	v_add_f32_e32 v136, 1.0, v136
	v_add_f32_e32 v137, 1.0, v137
	v_rcp_f32_e32 v134, v134
	v_rcp_f32_e32 v135, v135
	v_rcp_f32_e32 v136, v136
	v_rcp_f32_e32 v137, v137
	s_nop 0
	v_pk_mul_f32 v[128:129], v[128:129], v[134:135]
	v_pk_mul_f32 v[130:131], v[130:131], v[136:137]
	v_fmac_f32_e32 v206, v128, v128
	v_fmac_f32_e32 v206, v129, v129
	v_fmac_f32_e32 v206, v130, v130
	v_fmac_f32_e32 v206, v131, v131
	v_cvt_pk_bf16_f32 v132, v128, v129
	v_cvt_pk_bf16_f32 v133, v130, v131
	ds_write_b16 v208, v132
	ds_write_b16_d16_hi v208, v132 offset:80
	ds_write_b16 v208, v133 offset:160
	ds_write_b16_d16_hi v208, v133 offset:240
	v_pk_mul_f32 v[128:129], v[16:17], v[156:157] op_sel_hi:[1,0]
	v_pk_mul_f32 v[130:131], v[18:19], v[156:157] op_sel_hi:[1,0]
	v_mul_f32_e32 v134, 0x3d372713, v128
	v_mul_f32_e32 v135, 0x3d372713, v129
	v_mul_f32_e32 v136, 0x3d372713, v130
	v_mul_f32_e32 v137, 0x3d372713, v131
	v_mul_f32_e32 v134, v128, v134
	v_mul_f32_e32 v135, v129, v135
	v_mul_f32_e32 v136, v130, v136
	v_mul_f32_e32 v137, v131, v137
	v_fma_f32 v134, v128, v134, v128
	v_fma_f32 v135, v129, v135, v129
	v_fma_f32 v136, v130, v136, v130
	v_fma_f32 v137, v131, v137, v131
	v_mul_f32_e32 v134, 0x3fcc422a, v134
	v_mul_f32_e32 v135, 0x3fcc422a, v135
	v_mul_f32_e32 v136, 0x3fcc422a, v136
	v_mul_f32_e32 v137, 0x3fcc422a, v137
	v_mul_f32_e32 v134, 0xbfb8aa3b, v134
	v_mul_f32_e32 v135, 0xbfb8aa3b, v135
	v_mul_f32_e32 v136, 0xbfb8aa3b, v136
	v_mul_f32_e32 v137, 0xbfb8aa3b, v137
	v_exp_f32_e32 v134, v134
	v_exp_f32_e32 v135, v135
	v_exp_f32_e32 v136, v136
	v_exp_f32_e32 v137, v137
	v_add_f32_e32 v134, 1.0, v134
	v_add_f32_e32 v135, 1.0, v135
	v_add_f32_e32 v136, 1.0, v136
	v_add_f32_e32 v137, 1.0, v137
	v_rcp_f32_e32 v134, v134
	v_rcp_f32_e32 v135, v135
	v_rcp_f32_e32 v136, v136
	v_rcp_f32_e32 v137, v137
	s_nop 0
	v_pk_mul_f32 v[128:129], v[128:129], v[134:135]
	v_pk_mul_f32 v[130:131], v[130:131], v[136:137]
	v_fmac_f32_e32 v206, v128, v128
	v_fmac_f32_e32 v206, v129, v129
	v_fmac_f32_e32 v206, v130, v130
	v_fmac_f32_e32 v206, v131, v131
	v_cvt_pk_bf16_f32 v132, v128, v129
	v_cvt_pk_bf16_f32 v133, v130, v131
	ds_write_b16 v208, v132 offset:1280
	ds_write_b16_d16_hi v208, v132 offset:1360
	ds_write_b16 v208, v133 offset:1440
	ds_write_b16_d16_hi v208, v133 offset:1520
	v_pk_mul_f32 v[128:129], v[4:5], v[152:153] op_sel_hi:[1,0]
	v_pk_mul_f32 v[130:131], v[6:7], v[152:153] op_sel_hi:[1,0]
	v_mul_f32_e32 v134, 0x3d372713, v128
	v_mul_f32_e32 v135, 0x3d372713, v129
	v_mul_f32_e32 v136, 0x3d372713, v130
	v_mul_f32_e32 v137, 0x3d372713, v131
	v_mul_f32_e32 v134, v128, v134
	v_mul_f32_e32 v135, v129, v135
	v_mul_f32_e32 v136, v130, v136
	v_mul_f32_e32 v137, v131, v137
	v_fma_f32 v134, v128, v134, v128
	v_fma_f32 v135, v129, v135, v129
	v_fma_f32 v136, v130, v136, v130
	v_fma_f32 v137, v131, v137, v131
	v_mul_f32_e32 v134, 0x3fcc422a, v134
	v_mul_f32_e32 v135, 0x3fcc422a, v135
	v_mul_f32_e32 v136, 0x3fcc422a, v136
	v_mul_f32_e32 v137, 0x3fcc422a, v137
	v_mul_f32_e32 v134, 0xbfb8aa3b, v134
	v_mul_f32_e32 v135, 0xbfb8aa3b, v135
	v_mul_f32_e32 v136, 0xbfb8aa3b, v136
	v_mul_f32_e32 v137, 0xbfb8aa3b, v137
	v_exp_f32_e32 v134, v134
	v_exp_f32_e32 v135, v135
	v_exp_f32_e32 v136, v136
	v_exp_f32_e32 v137, v137
	v_add_f32_e32 v134, 1.0, v134
	v_add_f32_e32 v135, 1.0, v135
	v_add_f32_e32 v136, 1.0, v136
	v_add_f32_e32 v137, 1.0, v137
	v_rcp_f32_e32 v134, v134
	v_rcp_f32_e32 v135, v135
	v_rcp_f32_e32 v136, v136
	v_rcp_f32_e32 v137, v137
	s_nop 0
	v_pk_mul_f32 v[128:129], v[128:129], v[134:135]
	v_pk_mul_f32 v[130:131], v[130:131], v[136:137]
	v_fmac_f32_e32 v207, v128, v128
	v_fmac_f32_e32 v207, v129, v129
	v_fmac_f32_e32 v207, v130, v130
	v_fmac_f32_e32 v207, v131, v131
	v_cvt_pk_bf16_f32 v132, v128, v129
	v_cvt_pk_bf16_f32 v133, v130, v131
	ds_write_b16 v208, v132 offset:32
	ds_write_b16_d16_hi v208, v132 offset:112
	ds_write_b16 v208, v133 offset:192
	ds_write_b16_d16_hi v208, v133 offset:272
	v_pk_mul_f32 v[128:129], v[0:1], v[152:153] op_sel_hi:[1,0]
	v_pk_mul_f32 v[130:131], v[2:3], v[152:153] op_sel_hi:[1,0]
	v_mul_f32_e32 v134, 0x3d372713, v128
	v_mul_f32_e32 v135, 0x3d372713, v129
	v_mul_f32_e32 v136, 0x3d372713, v130
	v_mul_f32_e32 v137, 0x3d372713, v131
	v_mul_f32_e32 v134, v128, v134
	v_mul_f32_e32 v135, v129, v135
	v_mul_f32_e32 v136, v130, v136
	v_mul_f32_e32 v137, v131, v137
	v_fma_f32 v134, v128, v134, v128
	v_fma_f32 v135, v129, v135, v129
	v_fma_f32 v136, v130, v136, v130
	v_fma_f32 v137, v131, v137, v131
	v_mul_f32_e32 v134, 0x3fcc422a, v134
	v_mul_f32_e32 v135, 0x3fcc422a, v135
	v_mul_f32_e32 v136, 0x3fcc422a, v136
	v_mul_f32_e32 v137, 0x3fcc422a, v137
	v_mul_f32_e32 v134, 0xbfb8aa3b, v134
	v_mul_f32_e32 v135, 0xbfb8aa3b, v135
	v_mul_f32_e32 v136, 0xbfb8aa3b, v136
	v_mul_f32_e32 v137, 0xbfb8aa3b, v137
	v_exp_f32_e32 v134, v134
	v_exp_f32_e32 v135, v135
	v_exp_f32_e32 v136, v136
	v_exp_f32_e32 v137, v137
	v_add_f32_e32 v134, 1.0, v134
	v_add_f32_e32 v135, 1.0, v135
	v_add_f32_e32 v136, 1.0, v136
	v_add_f32_e32 v137, 1.0, v137
	v_rcp_f32_e32 v134, v134
	v_rcp_f32_e32 v135, v135
	v_rcp_f32_e32 v136, v136
	v_rcp_f32_e32 v137, v137
	s_nop 0
	v_pk_mul_f32 v[128:129], v[128:129], v[134:135]
	v_pk_mul_f32 v[130:131], v[130:131], v[136:137]
	v_fmac_f32_e32 v207, v128, v128
	v_fmac_f32_e32 v207, v129, v129
	v_fmac_f32_e32 v207, v130, v130
	v_fmac_f32_e32 v207, v131, v131
	v_cvt_pk_bf16_f32 v132, v128, v129
	v_cvt_pk_bf16_f32 v133, v130, v131
	ds_write_b16 v208, v132 offset:1312
	ds_write_b16_d16_hi v208, v132 offset:1392
	ds_write_b16 v208, v133 offset:1472
	ds_write_b16_d16_hi v208, v133 offset:1552
	s_waitcnt lgkmcnt(0)
	ds_read_b128 v[212:215], v209
	ds_read_b128 v[216:219], v209 offset:1280
	s_add_u32 s46, s44, s38
	s_addc_u32 s47, s45, 0
	s_add_u32 s46, s46, s100
	s_addc_u32 s47, s47, 0
	s_waitcnt lgkmcnt(0)
	global_store_dwordx4 v210, v[212:215], s[46:47] offset:64
	global_store_dwordx4 v211, v[216:219], s[46:47] offset:64
	ds_bpermute_b32 v212, v242, v200
	ds_bpermute_b32 v213, v242, v201
	ds_bpermute_b32 v214, v242, v202
	ds_bpermute_b32 v215, v242, v203
	ds_bpermute_b32 v216, v242, v204
	ds_bpermute_b32 v217, v242, v205
	ds_bpermute_b32 v218, v242, v206
	ds_bpermute_b32 v219, v242, v207
	s_waitcnt lgkmcnt(0)
	v_add_f32_e32 v200, v200, v212
	v_add_f32_e32 v201, v201, v213
	v_add_f32_e32 v202, v202, v214
	v_add_f32_e32 v203, v203, v215
	v_add_f32_e32 v204, v204, v216
	v_add_f32_e32 v205, v205, v217
	v_add_f32_e32 v206, v206, v218
	v_add_f32_e32 v207, v207, v219
	ds_bpermute_b32 v212, v243, v200
	ds_bpermute_b32 v213, v243, v201
	ds_bpermute_b32 v214, v243, v202
	ds_bpermute_b32 v215, v243, v203
	ds_bpermute_b32 v216, v243, v204
	ds_bpermute_b32 v217, v243, v205
	ds_bpermute_b32 v218, v243, v206
	ds_bpermute_b32 v219, v243, v207
	s_waitcnt lgkmcnt(0)
	v_add_f32_e32 v200, v200, v212
	v_add_f32_e32 v201, v201, v213
	v_add_f32_e32 v202, v202, v214
	v_add_f32_e32 v203, v203, v215
	v_add_f32_e32 v204, v204, v216
	v_add_f32_e32 v205, v205, v217
	v_add_f32_e32 v206, v206, v218
	v_add_f32_e32 v207, v207, v219
	v_cmp_eq_u32_e32 vcc, 0, v239
	s_and_saveexec_b64 s[46:47], vcc
	global_atomic_add_f32 v221, v200, s[50:51]
	global_atomic_add_f32 v221, v201, s[50:51] offset:64
	global_atomic_add_f32 v221, v202, s[50:51] offset:128
	global_atomic_add_f32 v221, v203, s[50:51] offset:192
	global_atomic_add_f32 v221, v204, s[50:51] offset:512
	global_atomic_add_f32 v221, v205, s[50:51] offset:576
	global_atomic_add_f32 v221, v206, s[50:51] offset:640
	global_atomic_add_f32 v221, v207, s[50:51] offset:704
	s_or_b64 exec, exec, s[46:47]
	s_branch .LBB0_586
.Ltr_k1:
	s_add_u32 s44, s69, s38
	s_addc_u32 s45, s70, 0
	s_mov_b32 s100, 0
	s_lshl_b32 s101, s28, 9
	s_add_i32 s101, s101, s31
	s_mul_i32 s101, s101, s39
	s_add_i32 s101, s101, s100
	s_lshl_b32 s38, s29, 1
	s_add_i32 s101, s101, s38
	s_add_i32 s28, s28, s23
	s_add_i32 s29, s29, s35
	s_lshl_b32 s38, s28, 9
	s_add_i32 s38, s38, s31
	s_mul_i32 s38, s38, s39
	s_add_i32 s38, s38, s100
	s_lshl_b32 s28, s29, 1
	s_add_i32 s38, s38, s28
	s_lshl_b32 s100, s39, 7
	v_lshrrev_b32_e32 v244, 6, v224
	v_mul_u32_u24_e32 v244, 2560, v244
	v_add_u32_e32 v244, 0x20000, v244
	v_mul_u32_u24_e32 v208, 320, v239
	v_lshl_add_u32 v208, v238, 1, v208
	v_add_u32_e32 v208, v208, v244
	v_and_b32_e32 v210, 63, v229
	v_lshrrev_b32_e32 v211, 2, v210
	v_and_b32_e32 v210, 3, v210
	v_mul_u32_u24_e32 v209, 80, v211
	v_lshl_add_u32 v209, v210, 4, v209
	v_add_u32_e32 v209, v209, v244
	v_mul_lo_u32 v211, v211, s39
	v_lshl_add_u32 v210, v210, 4, v211
	s_lshl_b32 s28, s39, 4
	v_add_u32_e32 v211, s28, v210
	v_pk_mul_f32 v[128:129], v[124:125], v[194:195] op_sel_hi:[1,0]
	v_pk_mul_f32 v[130:131], v[126:127], v[194:195] op_sel_hi:[1,0]
	v_cvt_pk_bf16_f32 v132, v128, v129
	v_cvt_pk_bf16_f32 v133, v130, v131
	ds_write_b16 v208, v132
	ds_write_b16_d16_hi v208, v132 offset:80
	ds_write_b16 v208, v133 offset:160
	ds_write_b16_d16_hi v208, v133 offset:240
	v_pk_mul_f32 v[128:129], v[120:121], v[194:195] op_sel_hi:[1,0]
	v_pk_mul_f32 v[130:131], v[122:123], v[194:195] op_sel_hi:[1,0]
	v_cvt_pk_bf16_f32 v132, v128, v129
	v_cvt_pk_bf16_f32 v133, v130, v131
	ds_write_b16 v208, v132 offset:1280
	ds_write_b16_d16_hi v208, v132 offset:1360
	ds_write_b16 v208, v133 offset:1440
	ds_write_b16_d16_hi v208, v133 offset:1520
	v_pk_mul_f32 v[128:129], v[108:109], v[190:191] op_sel_hi:[1,0]
	v_pk_mul_f32 v[130:131], v[110:111], v[190:191] op_sel_hi:[1,0]
	v_cvt_pk_bf16_f32 v132, v128, v129
	v_cvt_pk_bf16_f32 v133, v130, v131
	ds_write_b16 v208, v132 offset:32
	ds_write_b16_d16_hi v208, v132 offset:112
	ds_write_b16 v208, v133 offset:192
	ds_write_b16_d16_hi v208, v133 offset:272
	v_pk_mul_f32 v[128:129], v[104:105], v[190:191] op_sel_hi:[1,0]
	v_pk_mul_f32 v[130:131], v[106:107], v[190:191] op_sel_hi:[1,0]
	v_cvt_pk_bf16_f32 v132, v128, v129
	v_cvt_pk_bf16_f32 v133, v130, v131
	ds_write_b16 v208, v132 offset:1312
	ds_write_b16_d16_hi v208, v132 offset:1392
	ds_write_b16 v208, v133 offset:1472
	ds_write_b16_d16_hi v208, v133 offset:1552
	s_waitcnt lgkmcnt(0)
	ds_read_b128 v[212:215], v209
	ds_read_b128 v[216:219], v209 offset:1280
	s_add_u32 s46, s44, s101
	s_addc_u32 s47, s45, 0
	s_waitcnt lgkmcnt(0)
	global_store_dwordx4 v210, v[212:215], s[46:47]
	global_store_dwordx4 v211, v[216:219], s[46:47]
	v_pk_mul_f32 v[128:129], v[92:93], v[172:173] op_sel_hi:[1,0]
	v_pk_mul_f32 v[130:131], v[94:95], v[172:173] op_sel_hi:[1,0]
	v_cvt_pk_bf16_f32 v132, v128, v129
	v_cvt_pk_bf16_f32 v133, v130, v131
	ds_write_b16 v208, v132
	ds_write_b16_d16_hi v208, v132 offset:80
	ds_write_b16 v208, v133 offset:160
	ds_write_b16_d16_hi v208, v133 offset:240
	v_pk_mul_f32 v[128:129], v[88:89], v[172:173] op_sel_hi:[1,0]
	v_pk_mul_f32 v[130:131], v[90:91], v[172:173] op_sel_hi:[1,0]
	v_cvt_pk_bf16_f32 v132, v128, v129
	v_cvt_pk_bf16_f32 v133, v130, v131
	ds_write_b16 v208, v132 offset:1280
	ds_write_b16_d16_hi v208, v132 offset:1360
	ds_write_b16 v208, v133 offset:1440
	ds_write_b16_d16_hi v208, v133 offset:1520
	v_pk_mul_f32 v[128:129], v[76:77], v[168:169] op_sel_hi:[1,0]
	v_pk_mul_f32 v[130:131], v[78:79], v[168:169] op_sel_hi:[1,0]
	v_cvt_pk_bf16_f32 v132, v128, v129
	v_cvt_pk_bf16_f32 v133, v130, v131
	ds_write_b16 v208, v132 offset:32
	ds_write_b16_d16_hi v208, v132 offset:112
	ds_write_b16 v208, v133 offset:192
	ds_write_b16_d16_hi v208, v133 offset:272
	v_pk_mul_f32 v[128:129], v[72:73], v[168:169] op_sel_hi:[1,0]
	v_pk_mul_f32 v[130:131], v[74:75], v[168:169] op_sel_hi:[1,0]
	v_cvt_pk_bf16_f32 v132, v128, v129
	v_cvt_pk_bf16_f32 v133, v130, v131
	ds_write_b16 v208, v132 offset:1312
	ds_write_b16_d16_hi v208, v132 offset:1392
	ds_write_b16 v208, v133 offset:1472
	ds_write_b16_d16_hi v208, v133 offset:1552
	s_waitcnt lgkmcnt(0)
	ds_read_b128 v[212:215], v209
	ds_read_b128 v[216:219], v209 offset:1280
	s_add_u32 s46, s44, s101
	s_addc_u32 s47, s45, 0
	s_waitcnt lgkmcnt(0)
	global_store_dwordx4 v210, v[212:215], s[46:47] offset:64
	global_store_dwordx4 v211, v[216:219], s[46:47] offset:64
	v_pk_mul_f32 v[128:129], v[116:117], v[194:195] op_sel_hi:[1,0]
	v_pk_mul_f32 v[130:131], v[118:119], v[194:195] op_sel_hi:[1,0]
	v_cvt_pk_bf16_f32 v132, v128, v129
	v_cvt_pk_bf16_f32 v133, v130, v131
	ds_write_b16 v208, v132
	ds_write_b16_d16_hi v208, v132 offset:80
	ds_write_b16 v208, v133 offset:160
	ds_write_b16_d16_hi v208, v133 offset:240
	v_pk_mul_f32 v[128:129], v[112:113], v[194:195] op_sel_hi:[1,0]
	v_pk_mul_f32 v[130:131], v[114:115], v[194:195] op_sel_hi:[1,0]
	v_cvt_pk_bf16_f32 v132, v128, v129
	v_cvt_pk_bf16_f32 v133, v130, v131
	ds_write_b16 v208, v132 offset:1280
	ds_write_b16_d16_hi v208, v132 offset:1360
	ds_write_b16 v208, v133 offset:1440
	ds_write_b16_d16_hi v208, v133 offset:1520
	v_pk_mul_f32 v[128:129], v[100:101], v[190:191] op_sel_hi:[1,0]
	v_pk_mul_f32 v[130:131], v[102:103], v[190:191] op_sel_hi:[1,0]
	v_cvt_pk_bf16_f32 v132, v128, v129
	v_cvt_pk_bf16_f32 v133, v130, v131
	ds_write_b16 v208, v132 offset:32
	ds_write_b16_d16_hi v208, v132 offset:112
	ds_write_b16 v208, v133 offset:192
	ds_write_b16_d16_hi v208, v133 offset:272
	v_pk_mul_f32 v[128:129], v[96:97], v[190:191] op_sel_hi:[1,0]
	v_pk_mul_f32 v[130:131], v[98:99], v[190:191] op_sel_hi:[1,0]
	v_cvt_pk_bf16_f32 v132, v128, v129
	v_cvt_pk_bf16_f32 v133, v130, v131
	ds_write_b16 v208, v132 offset:1312
	ds_write_b16_d16_hi v208, v132 offset:1392
	ds_write_b16 v208, v133 offset:1472
	ds_write_b16_d16_hi v208, v133 offset:1552
	s_waitcnt lgkmcnt(0)
	ds_read_b128 v[212:215], v209
	ds_read_b128 v[216:219], v209 offset:1280
	s_add_u32 s46, s44, s101
	s_addc_u32 s47, s45, 0
	s_add_u32 s46, s46, s100
	s_addc_u32 s47, s47, 0
	s_waitcnt lgkmcnt(0)
	global_store_dwordx4 v210, v[212:215], s[46:47]
	global_store_dwordx4 v211, v[216:219], s[46:47]
	v_pk_mul_f32 v[128:129], v[84:85], v[172:173] op_sel_hi:[1,0]
	v_pk_mul_f32 v[130:131], v[86:87], v[172:173] op_sel_hi:[1,0]
	v_cvt_pk_bf16_f32 v132, v128, v129
	v_cvt_pk_bf16_f32 v133, v130, v131
	ds_write_b16 v208, v132
	ds_write_b16_d16_hi v208, v132 offset:80
	ds_write_b16 v208, v133 offset:160
	ds_write_b16_d16_hi v208, v133 offset:240
	v_pk_mul_f32 v[128:129], v[80:81], v[172:173] op_sel_hi:[1,0]
	v_pk_mul_f32 v[130:131], v[82:83], v[172:173] op_sel_hi:[1,0]
	v_cvt_pk_bf16_f32 v132, v128, v129
	v_cvt_pk_bf16_f32 v133, v130, v131
	ds_write_b16 v208, v132 offset:1280
	ds_write_b16_d16_hi v208, v132 offset:1360
	ds_write_b16 v208, v133 offset:1440
	ds_write_b16_d16_hi v208, v133 offset:1520
	v_pk_mul_f32 v[128:129], v[68:69], v[168:169] op_sel_hi:[1,0]
	v_pk_mul_f32 v[130:131], v[70:71], v[168:169] op_sel_hi:[1,0]
	v_cvt_pk_bf16_f32 v132, v128, v129
	v_cvt_pk_bf16_f32 v133, v130, v131
	ds_write_b16 v208, v132 offset:32
	ds_write_b16_d16_hi v208, v132 offset:112
	ds_write_b16 v208, v133 offset:192
	ds_write_b16_d16_hi v208, v133 offset:272
	v_pk_mul_f32 v[128:129], v[64:65], v[168:169] op_sel_hi:[1,0]
	v_pk_mul_f32 v[130:131], v[66:67], v[168:169] op_sel_hi:[1,0]
	v_cvt_pk_bf16_f32 v132, v128, v129
	v_cvt_pk_bf16_f32 v133, v130, v131
	ds_write_b16 v208, v132 offset:1312
	ds_write_b16_d16_hi v208, v132 offset:1392
	ds_write_b16 v208, v133 offset:1472
	ds_write_b16_d16_hi v208, v133 offset:1552
	s_waitcnt lgkmcnt(0)
	ds_read_b128 v[212:215], v209
	ds_read_b128 v[216:219], v209 offset:1280
	s_add_u32 s46, s44, s101
	s_addc_u32 s47, s45, 0
	s_add_u32 s46, s46, s100
	s_addc_u32 s47, s47, 0
	s_waitcnt lgkmcnt(0)
	global_store_dwordx4 v210, v[212:215], s[46:47] offset:64
	global_store_dwordx4 v211, v[216:219], s[46:47] offset:64
	v_pk_mul_f32 v[128:129], v[60:61], v[164:165] op_sel_hi:[1,0]
	v_pk_mul_f32 v[130:131], v[62:63], v[164:165] op_sel_hi:[1,0]
	v_cvt_pk_bf16_f32 v132, v128, v129
	v_cvt_pk_bf16_f32 v133, v130, v131
	ds_write_b16 v208, v132
	ds_write_b16_d16_hi v208, v132 offset:80
	ds_write_b16 v208, v133 offset:160
	ds_write_b16_d16_hi v208, v133 offset:240
	v_pk_mul_f32 v[128:129], v[56:57], v[164:165] op_sel_hi:[1,0]
	v_pk_mul_f32 v[130:131], v[58:59], v[164:165] op_sel_hi:[1,0]
	v_cvt_pk_bf16_f32 v132, v128, v129
	v_cvt_pk_bf16_f32 v133, v130, v131
	ds_write_b16 v208, v132 offset:1280
	ds_write_b16_d16_hi v208, v132 offset:1360
	ds_write_b16 v208, v133 offset:1440
	ds_write_b16_d16_hi v208, v133 offset:1520
	v_pk_mul_f32 v[128:129], v[44:45], v[160:161] op_sel_hi:[1,0]
	v_pk_mul_f32 v[130:131], v[46:47], v[160:161] op_sel_hi:[1,0]
	v_cvt_pk_bf16_f32 v132, v128, v129
	v_cvt_pk_bf16_f32 v133, v130, v131
	ds_write_b16 v208, v132 offset:32
	ds_write_b16_d16_hi v208, v132 offset:112
	ds_write_b16 v208, v133 offset:192
	ds_write_b16_d16_hi v208, v133 offset:272
	v_pk_mul_f32 v[128:129], v[40:41], v[160:161] op_sel_hi:[1,0]
	v_pk_mul_f32 v[130:131], v[42:43], v[160:161] op_sel_hi:[1,0]
	v_cvt_pk_bf16_f32 v132, v128, v129
	v_cvt_pk_bf16_f32 v133, v130, v131
	ds_write_b16 v208, v132 offset:1312
	ds_write_b16_d16_hi v208, v132 offset:1392
	ds_write_b16 v208, v133 offset:1472
	ds_write_b16_d16_hi v208, v133 offset:1552
	s_waitcnt lgkmcnt(0)
	ds_read_b128 v[212:215], v209
	ds_read_b128 v[216:219], v209 offset:1280
	s_add_u32 s46, s44, s38
	s_addc_u32 s47, s45, 0
	s_waitcnt lgkmcnt(0)
	global_store_dwordx4 v210, v[212:215], s[46:47]
	global_store_dwordx4 v211, v[216:219], s[46:47]
	v_pk_mul_f32 v[128:129], v[28:29], v[156:157] op_sel_hi:[1,0]
	v_pk_mul_f32 v[130:131], v[30:31], v[156:157] op_sel_hi:[1,0]
	v_cvt_pk_bf16_f32 v132, v128, v129
	v_cvt_pk_bf16_f32 v133, v130, v131
	ds_write_b16 v208, v132
	ds_write_b16_d16_hi v208, v132 offset:80
	ds_write_b16 v208, v133 offset:160
	ds_write_b16_d16_hi v208, v133 offset:240
	v_pk_mul_f32 v[128:129], v[24:25], v[156:157] op_sel_hi:[1,0]
	v_pk_mul_f32 v[130:131], v[26:27], v[156:157] op_sel_hi:[1,0]
	v_cvt_pk_bf16_f32 v132, v128, v129
	v_cvt_pk_bf16_f32 v133, v130, v131
	ds_write_b16 v208, v132 offset:1280
	ds_write_b16_d16_hi v208, v132 offset:1360
	ds_write_b16 v208, v133 offset:1440
	ds_write_b16_d16_hi v208, v133 offset:1520
	v_pk_mul_f32 v[128:129], v[12:13], v[152:153] op_sel_hi:[1,0]
	v_pk_mul_f32 v[130:131], v[14:15], v[152:153] op_sel_hi:[1,0]
	v_cvt_pk_bf16_f32 v132, v128, v129
	v_cvt_pk_bf16_f32 v133, v130, v131
	ds_write_b16 v208, v132 offset:32
	ds_write_b16_d16_hi v208, v132 offset:112
	ds_write_b16 v208, v133 offset:192
	ds_write_b16_d16_hi v208, v133 offset:272
	v_pk_mul_f32 v[128:129], v[8:9], v[152:153] op_sel_hi:[1,0]
	v_pk_mul_f32 v[130:131], v[10:11], v[152:153] op_sel_hi:[1,0]
	v_cvt_pk_bf16_f32 v132, v128, v129
	v_cvt_pk_bf16_f32 v133, v130, v131
	ds_write_b16 v208, v132 offset:1312
	ds_write_b16_d16_hi v208, v132 offset:1392
	ds_write_b16 v208, v133 offset:1472
	ds_write_b16_d16_hi v208, v133 offset:1552
	s_waitcnt lgkmcnt(0)
	ds_read_b128 v[212:215], v209
	ds_read_b128 v[216:219], v209 offset:1280
	s_add_u32 s46, s44, s38
	s_addc_u32 s47, s45, 0
	s_waitcnt lgkmcnt(0)
	global_store_dwordx4 v210, v[212:215], s[46:47] offset:64
	global_store_dwordx4 v211, v[216:219], s[46:47] offset:64
	v_pk_mul_f32 v[128:129], v[52:53], v[164:165] op_sel_hi:[1,0]
	v_pk_mul_f32 v[130:131], v[54:55], v[164:165] op_sel_hi:[1,0]
	v_cvt_pk_bf16_f32 v132, v128, v129
	v_cvt_pk_bf16_f32 v133, v130, v131
	ds_write_b16 v208, v132
	ds_write_b16_d16_hi v208, v132 offset:80
	ds_write_b16 v208, v133 offset:160
	ds_write_b16_d16_hi v208, v133 offset:240
	v_pk_mul_f32 v[128:129], v[48:49], v[164:165] op_sel_hi:[1,0]
	v_pk_mul_f32 v[130:131], v[50:51], v[164:165] op_sel_hi:[1,0]
	v_cvt_pk_bf16_f32 v132, v128, v129
	v_cvt_pk_bf16_f32 v133, v130, v131
	ds_write_b16 v208, v132 offset:1280
	ds_write_b16_d16_hi v208, v132 offset:1360
	ds_write_b16 v208, v133 offset:1440
	ds_write_b16_d16_hi v208, v133 offset:1520
	v_pk_mul_f32 v[128:129], v[36:37], v[160:161] op_sel_hi:[1,0]
	v_pk_mul_f32 v[130:131], v[38:39], v[160:161] op_sel_hi:[1,0]
	v_cvt_pk_bf16_f32 v132, v128, v129
	v_cvt_pk_bf16_f32 v133, v130, v131
	ds_write_b16 v208, v132 offset:32
	ds_write_b16_d16_hi v208, v132 offset:112
	ds_write_b16 v208, v133 offset:192
	ds_write_b16_d16_hi v208, v133 offset:272
	v_pk_mul_f32 v[128:129], v[32:33], v[160:161] op_sel_hi:[1,0]
	v_pk_mul_f32 v[130:131], v[34:35], v[160:161] op_sel_hi:[1,0]
	v_cvt_pk_bf16_f32 v132, v128, v129
	v_cvt_pk_bf16_f32 v133, v130, v131
	ds_write_b16 v208, v132 offset:1312
	ds_write_b16_d16_hi v208, v132 offset:1392
	ds_write_b16 v208, v133 offset:1472
	ds_write_b16_d16_hi v208, v133 offset:1552
	s_waitcnt lgkmcnt(0)
	ds_read_b128 v[212:215], v209
	ds_read_b128 v[216:219], v209 offset:1280
	s_add_u32 s46, s44, s38
	s_addc_u32 s47, s45, 0
	s_add_u32 s46, s46, s100
	s_addc_u32 s47, s47, 0
	s_waitcnt lgkmcnt(0)
	global_store_dwordx4 v210, v[212:215], s[46:47]
	global_store_dwordx4 v211, v[216:219], s[46:47]
	v_pk_mul_f32 v[128:129], v[20:21], v[156:157] op_sel_hi:[1,0]
	v_pk_mul_f32 v[130:131], v[22:23], v[156:157] op_sel_hi:[1,0]
	v_cvt_pk_bf16_f32 v132, v128, v129
	v_cvt_pk_bf16_f32 v133, v130, v131
	ds_write_b16 v208, v132
	ds_write_b16_d16_hi v208, v132 offset:80
	ds_write_b16 v208, v133 offset:160
	ds_write_b16_d16_hi v208, v133 offset:240
	v_pk_mul_f32 v[128:129], v[16:17], v[156:157] op_sel_hi:[1,0]
	v_pk_mul_f32 v[130:131], v[18:19], v[156:157] op_sel_hi:[1,0]
	v_cvt_pk_bf16_f32 v132, v128, v129
	v_cvt_pk_bf16_f32 v133, v130, v131
	ds_write_b16 v208, v132 offset:1280
	ds_write_b16_d16_hi v208, v132 offset:1360
	ds_write_b16 v208, v133 offset:1440
	ds_write_b16_d16_hi v208, v133 offset:1520
	v_pk_mul_f32 v[128:129], v[4:5], v[152:153] op_sel_hi:[1,0]
	v_pk_mul_f32 v[130:131], v[6:7], v[152:153] op_sel_hi:[1,0]
	v_cvt_pk_bf16_f32 v132, v128, v129
	v_cvt_pk_bf16_f32 v133, v130, v131
	ds_write_b16 v208, v132 offset:32
	ds_write_b16_d16_hi v208, v132 offset:112
	ds_write_b16 v208, v133 offset:192
	ds_write_b16_d16_hi v208, v133 offset:272
	v_pk_mul_f32 v[128:129], v[0:1], v[152:153] op_sel_hi:[1,0]
	v_pk_mul_f32 v[130:131], v[2:3], v[152:153] op_sel_hi:[1,0]
	v_cvt_pk_bf16_f32 v132, v128, v129
	v_cvt_pk_bf16_f32 v133, v130, v131
	ds_write_b16 v208, v132 offset:1312
	ds_write_b16_d16_hi v208, v132 offset:1392
	ds_write_b16 v208, v133 offset:1472
	ds_write_b16_d16_hi v208, v133 offset:1552
	s_waitcnt lgkmcnt(0)
	ds_read_b128 v[212:215], v209
	ds_read_b128 v[216:219], v209 offset:1280
	s_add_u32 s46, s44, s38
	s_addc_u32 s47, s45, 0
	s_add_u32 s46, s46, s100
	s_addc_u32 s47, s47, 0
	s_waitcnt lgkmcnt(0)
	global_store_dwordx4 v210, v[212:215], s[46:47] offset:64
	global_store_dwordx4 v211, v[216:219], s[46:47] offset:64
	s_branch .LBB0_586
.Ltr_k2:
	s_cmp_lg_u64 s[42:43], 0
	s_mov_b32 s38, 0x1a788000
	s_cselect_b32 s38, s38, 0x18788000
	s_movk_i32 s39, 0x1000
	s_cselect_b32 s39, 0x2080, s39
	s_cselect_b32 s100, 0x2000, 0
	s_add_u32 s44, s96, s38
	s_addc_u32 s45, s97, 0
	s_lshl_b32 s101, s28, 9
	s_add_i32 s101, s101, s31
	s_mul_i32 s101, s101, s39
	s_add_i32 s101, s101, s100
	s_lshl_b32 s38, s29, 1
	s_add_i32 s101, s101, s38
	s_add_i32 s28, s28, s23
	s_add_i32 s29, s29, s35
	s_lshl_b32 s38, s28, 9
	s_add_i32 s38, s38, s31
	s_mul_i32 s38, s38, s39
	s_add_i32 s38, s38, s100
	s_lshl_b32 s28, s29, 1
	s_add_i32 s38, s38, s28
	s_lshl_b32 s100, s39, 7
	v_lshrrev_b32_e32 v244, 6, v224
	v_mul_u32_u24_e32 v244, 2560, v244
	v_add_u32_e32 v244, 0x20000, v244
	v_mul_u32_u24_e32 v208, 320, v239
	v_lshl_add_u32 v208, v238, 1, v208
	v_add_u32_e32 v208, v208, v244
	v_and_b32_e32 v210, 63, v229
	v_lshrrev_b32_e32 v211, 2, v210
	v_and_b32_e32 v210, 3, v210
	v_mul_u32_u24_e32 v209, 80, v211
	v_lshl_add_u32 v209, v210, 4, v209
	v_add_u32_e32 v209, v209, v244
	v_mul_lo_u32 v211, v211, s39
	v_lshl_add_u32 v210, v210, 4, v211
	s_lshl_b32 s28, s39, 4
	v_add_u32_e32 v211, s28, v210
	v_subrev_u32_e32 v220, s86, v196
	v_lshlrev_b32_e32 v220, 11, v220
	s_and_b32 s28, s74, 1
	s_lshl_b32 s28, s28, 8
	v_add_u32_e32 v244, s28, v198
	v_lshl_add_u32 v220, v244, 2, v220
	v_pk_mul_f32 v[128:129], v[124:125], v[194:195] op_sel_hi:[1,0]
	v_pk_mul_f32 v[130:131], v[126:127], v[194:195] op_sel_hi:[1,0]
	global_store_dwordx4 v220, v[128:131], s[48:49]
	v_cvt_pk_bf16_f32 v132, v128, v129
	v_cvt_pk_bf16_f32 v133, v130, v131
	ds_write_b16 v208, v132
	ds_write_b16_d16_hi v208, v132 offset:80
	ds_write_b16 v208, v133 offset:160
	ds_write_b16_d16_hi v208, v133 offset:240
	v_pk_mul_f32 v[128:129], v[120:121], v[194:195] op_sel_hi:[1,0]
	v_pk_mul_f32 v[130:131], v[122:123], v[194:195] op_sel_hi:[1,0]
	global_store_dwordx4 v220, v[128:131], s[48:49] offset:64
	v_cvt_pk_bf16_f32 v132, v128, v129
	v_cvt_pk_bf16_f32 v133, v130, v131
	ds_write_b16 v208, v132 offset:1280
	ds_write_b16_d16_hi v208, v132 offset:1360
	ds_write_b16 v208, v133 offset:1440
	ds_write_b16_d16_hi v208, v133 offset:1520
	v_pk_mul_f32 v[128:129], v[108:109], v[190:191] op_sel_hi:[1,0]
	v_pk_mul_f32 v[130:131], v[110:111], v[190:191] op_sel_hi:[1,0]
	v_add_u32_e32 v244, 0x8000, v220
	global_store_dwordx4 v244, v[128:131], s[48:49]
	v_cvt_pk_bf16_f32 v132, v128, v129
	v_cvt_pk_bf16_f32 v133, v130, v131
	ds_write_b16 v208, v132 offset:32
	ds_write_b16_d16_hi v208, v132 offset:112
	ds_write_b16 v208, v133 offset:192
	ds_write_b16_d16_hi v208, v133 offset:272
	v_pk_mul_f32 v[128:129], v[104:105], v[190:191] op_sel_hi:[1,0]
	v_pk_mul_f32 v[130:131], v[106:107], v[190:191] op_sel_hi:[1,0]
	v_add_u32_e32 v244, 0x8000, v220
	global_store_dwordx4 v244, v[128:131], s[48:49] offset:64
	v_cvt_pk_bf16_f32 v132, v128, v129
	v_cvt_pk_bf16_f32 v133, v130, v131
	ds_write_b16 v208, v132 offset:1312
	ds_write_b16_d16_hi v208, v132 offset:1392
	ds_write_b16 v208, v133 offset:1472
	ds_write_b16_d16_hi v208, v133 offset:1552
	s_waitcnt lgkmcnt(0)
	ds_read_b128 v[212:215], v209
	ds_read_b128 v[216:219], v209 offset:1280
	s_add_u32 s46, s44, s101
	s_addc_u32 s47, s45, 0
	s_waitcnt lgkmcnt(0)
	global_store_dwordx4 v210, v[212:215], s[46:47]
	global_store_dwordx4 v211, v[216:219], s[46:47]
	v_pk_mul_f32 v[128:129], v[92:93], v[172:173] op_sel_hi:[1,0]
	v_pk_mul_f32 v[130:131], v[94:95], v[172:173] op_sel_hi:[1,0]
	v_add_u32_e32 v244, 0x10000, v220
	global_store_dwordx4 v244, v[128:131], s[48:49]
	v_cvt_pk_bf16_f32 v132, v128, v129
	v_cvt_pk_bf16_f32 v133, v130, v131
	ds_write_b16 v208, v132
	ds_write_b16_d16_hi v208, v132 offset:80
	ds_write_b16 v208, v133 offset:160
	ds_write_b16_d16_hi v208, v133 offset:240
	v_pk_mul_f32 v[128:129], v[88:89], v[172:173] op_sel_hi:[1,0]
	v_pk_mul_f32 v[130:131], v[90:91], v[172:173] op_sel_hi:[1,0]
	v_add_u32_e32 v244, 0x10000, v220
	global_store_dwordx4 v244, v[128:131], s[48:49] offset:64
	v_cvt_pk_bf16_f32 v132, v128, v129
	v_cvt_pk_bf16_f32 v133, v130, v131
	ds_write_b16 v208, v132 offset:1280
	ds_write_b16_d16_hi v208, v132 offset:1360
	ds_write_b16 v208, v133 offset:1440
	ds_write_b16_d16_hi v208, v133 offset:1520
	v_pk_mul_f32 v[128:129], v[76:77], v[168:169] op_sel_hi:[1,0]
	v_pk_mul_f32 v[130:131], v[78:79], v[168:169] op_sel_hi:[1,0]
	v_add_u32_e32 v244, 0x18000, v220
	global_store_dwordx4 v244, v[128:131], s[48:49]
	v_cvt_pk_bf16_f32 v132, v128, v129
	v_cvt_pk_bf16_f32 v133, v130, v131
	ds_write_b16 v208, v132 offset:32
	ds_write_b16_d16_hi v208, v132 offset:112
	ds_write_b16 v208, v133 offset:192
	ds_write_b16_d16_hi v208, v133 offset:272
	v_pk_mul_f32 v[128:129], v[72:73], v[168:169] op_sel_hi:[1,0]
	v_pk_mul_f32 v[130:131], v[74:75], v[168:169] op_sel_hi:[1,0]
	v_add_u32_e32 v244, 0x18000, v220
	global_store_dwordx4 v244, v[128:131], s[48:49] offset:64
	v_cvt_pk_bf16_f32 v132, v128, v129
	v_cvt_pk_bf16_f32 v133, v130, v131
	ds_write_b16 v208, v132 offset:1312
	ds_write_b16_d16_hi v208, v132 offset:1392
	ds_write_b16 v208, v133 offset:1472
	ds_write_b16_d16_hi v208, v133 offset:1552
	s_waitcnt lgkmcnt(0)
	ds_read_b128 v[212:215], v209
	ds_read_b128 v[216:219], v209 offset:1280
	s_add_u32 s46, s44, s101
	s_addc_u32 s47, s45, 0
	s_waitcnt lgkmcnt(0)
	global_store_dwordx4 v210, v[212:215], s[46:47] offset:64
	global_store_dwordx4 v211, v[216:219], s[46:47] offset:64
	v_pk_mul_f32 v[128:129], v[116:117], v[194:195] op_sel_hi:[1,0]
	v_pk_mul_f32 v[130:131], v[118:119], v[194:195] op_sel_hi:[1,0]
	global_store_dwordx4 v220, v[128:131], s[48:49] offset:512
	v_cvt_pk_bf16_f32 v132, v128, v129
	v_cvt_pk_bf16_f32 v133, v130, v131
	ds_write_b16 v208, v132
	ds_write_b16_d16_hi v208, v132 offset:80
	ds_write_b16 v208, v133 offset:160
	ds_write_b16_d16_hi v208, v133 offset:240
	v_pk_mul_f32 v[128:129], v[112:113], v[194:195] op_sel_hi:[1,0]
	v_pk_mul_f32 v[130:131], v[114:115], v[194:195] op_sel_hi:[1,0]
	global_store_dwordx4 v220, v[128:131], s[48:49] offset:576
	v_cvt_pk_bf16_f32 v132, v128, v129
	v_cvt_pk_bf16_f32 v133, v130, v131
	ds_write_b16 v208, v132 offset:1280
	ds_write_b16_d16_hi v208, v132 offset:1360
	ds_write_b16 v208, v133 offset:1440
	ds_write_b16_d16_hi v208, v133 offset:1520
	v_pk_mul_f32 v[128:129], v[100:101], v[190:191] op_sel_hi:[1,0]
	v_pk_mul_f32 v[130:131], v[102:103], v[190:191] op_sel_hi:[1,0]
	v_add_u32_e32 v244, 0x8000, v220
	global_store_dwordx4 v244, v[128:131], s[48:49] offset:512
	v_cvt_pk_bf16_f32 v132, v128, v129
	v_cvt_pk_bf16_f32 v133, v130, v131
	ds_write_b16 v208, v132 offset:32
	ds_write_b16_d16_hi v208, v132 offset:112
	ds_write_b16 v208, v133 offset:192
	ds_write_b16_d16_hi v208, v133 offset:272
	v_pk_mul_f32 v[128:129], v[96:97], v[190:191] op_sel_hi:[1,0]
	v_pk_mul_f32 v[130:131], v[98:99], v[190:191] op_sel_hi:[1,0]
	v_add_u32_e32 v244, 0x8000, v220
	global_store_dwordx4 v244, v[128:131], s[48:49] offset:576
	v_cvt_pk_bf16_f32 v132, v128, v129
	v_cvt_pk_bf16_f32 v133, v130, v131
	ds_write_b16 v208, v132 offset:1312
	ds_write_b16_d16_hi v208, v132 offset:1392
	ds_write_b16 v208, v133 offset:1472
	ds_write_b16_d16_hi v208, v133 offset:1552
	s_waitcnt lgkmcnt(0)
	ds_read_b128 v[212:215], v209
	ds_read_b128 v[216:219], v209 offset:1280
	s_add_u32 s46, s44, s101
	s_addc_u32 s47, s45, 0
	s_add_u32 s46, s46, s100
	s_addc_u32 s47, s47, 0
	s_waitcnt lgkmcnt(0)
	global_store_dwordx4 v210, v[212:215], s[46:47]
	global_store_dwordx4 v211, v[216:219], s[46:47]
	v_pk_mul_f32 v[128:129], v[84:85], v[172:173] op_sel_hi:[1,0]
	v_pk_mul_f32 v[130:131], v[86:87], v[172:173] op_sel_hi:[1,0]
	v_add_u32_e32 v244, 0x10000, v220
	global_store_dwordx4 v244, v[128:131], s[48:49] offset:512
	v_cvt_pk_bf16_f32 v132, v128, v129
	v_cvt_pk_bf16_f32 v133, v130, v131
	ds_write_b16 v208, v132
	ds_write_b16_d16_hi v208, v132 offset:80
	ds_write_b16 v208, v133 offset:160
	ds_write_b16_d16_hi v208, v133 offset:240
	v_pk_mul_f32 v[128:129], v[80:81], v[172:173] op_sel_hi:[1,0]
	v_pk_mul_f32 v[130:131], v[82:83], v[172:173] op_sel_hi:[1,0]
	v_add_u32_e32 v244, 0x10000, v220
	global_store_dwordx4 v244, v[128:131], s[48:49] offset:576
	v_cvt_pk_bf16_f32 v132, v128, v129
	v_cvt_pk_bf16_f32 v133, v130, v131
	ds_write_b16 v208, v132 offset:1280
	ds_write_b16_d16_hi v208, v132 offset:1360
	ds_write_b16 v208, v133 offset:1440
	ds_write_b16_d16_hi v208, v133 offset:1520
	v_pk_mul_f32 v[128:129], v[68:69], v[168:169] op_sel_hi:[1,0]
	v_pk_mul_f32 v[130:131], v[70:71], v[168:169] op_sel_hi:[1,0]
	v_add_u32_e32 v244, 0x18000, v220
	global_store_dwordx4 v244, v[128:131], s[48:49] offset:512
	v_cvt_pk_bf16_f32 v132, v128, v129
	v_cvt_pk_bf16_f32 v133, v130, v131
	ds_write_b16 v208, v132 offset:32
	ds_write_b16_d16_hi v208, v132 offset:112
	ds_write_b16 v208, v133 offset:192
	ds_write_b16_d16_hi v208, v133 offset:272
	v_pk_mul_f32 v[128:129], v[64:65], v[168:169] op_sel_hi:[1,0]
	v_pk_mul_f32 v[130:131], v[66:67], v[168:169] op_sel_hi:[1,0]
	v_add_u32_e32 v244, 0x18000, v220
	global_store_dwordx4 v244, v[128:131], s[48:49] offset:576
	v_cvt_pk_bf16_f32 v132, v128, v129
	v_cvt_pk_bf16_f32 v133, v130, v131
	ds_write_b16 v208, v132 offset:1312
	ds_write_b16_d16_hi v208, v132 offset:1392
	ds_write_b16 v208, v133 offset:1472
	ds_write_b16_d16_hi v208, v133 offset:1552
	s_waitcnt lgkmcnt(0)
	ds_read_b128 v[212:215], v209
	ds_read_b128 v[216:219], v209 offset:1280
	s_add_u32 s46, s44, s101
	s_addc_u32 s47, s45, 0
	s_add_u32 s46, s46, s100
	s_addc_u32 s47, s47, 0
	s_waitcnt lgkmcnt(0)
	global_store_dwordx4 v210, v[212:215], s[46:47] offset:64
	global_store_dwordx4 v211, v[216:219], s[46:47] offset:64
	v_pk_mul_f32 v[128:129], v[60:61], v[164:165] op_sel_hi:[1,0]
	v_pk_mul_f32 v[130:131], v[62:63], v[164:165] op_sel_hi:[1,0]
	v_add_u32_e32 v244, 0x40000, v220
	global_store_dwordx4 v244, v[128:131], s[48:49]
	v_cvt_pk_bf16_f32 v132, v128, v129
	v_cvt_pk_bf16_f32 v133, v130, v131
	ds_write_b16 v208, v132
	ds_write_b16_d16_hi v208, v132 offset:80
	ds_write_b16 v208, v133 offset:160
	ds_write_b16_d16_hi v208, v133 offset:240
	v_pk_mul_f32 v[128:129], v[56:57], v[164:165] op_sel_hi:[1,0]
	v_pk_mul_f32 v[130:131], v[58:59], v[164:165] op_sel_hi:[1,0]
	v_add_u32_e32 v244, 0x40000, v220
	global_store_dwordx4 v244, v[128:131], s[48:49] offset:64
	v_cvt_pk_bf16_f32 v132, v128, v129
	v_cvt_pk_bf16_f32 v133, v130, v131
	ds_write_b16 v208, v132 offset:1280
	ds_write_b16_d16_hi v208, v132 offset:1360
	ds_write_b16 v208, v133 offset:1440
	ds_write_b16_d16_hi v208, v133 offset:1520
	v_pk_mul_f32 v[128:129], v[44:45], v[160:161] op_sel_hi:[1,0]
	v_pk_mul_f32 v[130:131], v[46:47], v[160:161] op_sel_hi:[1,0]
	v_add_u32_e32 v244, 0x48000, v220
	global_store_dwordx4 v244, v[128:131], s[48:49]
	v_cvt_pk_bf16_f32 v132, v128, v129
	v_cvt_pk_bf16_f32 v133, v130, v131
	ds_write_b16 v208, v132 offset:32
	ds_write_b16_d16_hi v208, v132 offset:112
	ds_write_b16 v208, v133 offset:192
	ds_write_b16_d16_hi v208, v133 offset:272
	v_pk_mul_f32 v[128:129], v[40:41], v[160:161] op_sel_hi:[1,0]
	v_pk_mul_f32 v[130:131], v[42:43], v[160:161] op_sel_hi:[1,0]
	v_add_u32_e32 v244, 0x48000, v220
	global_store_dwordx4 v244, v[128:131], s[48:49] offset:64
	v_cvt_pk_bf16_f32 v132, v128, v129
	v_cvt_pk_bf16_f32 v133, v130, v131
	ds_write_b16 v208, v132 offset:1312
	ds_write_b16_d16_hi v208, v132 offset:1392
	ds_write_b16 v208, v133 offset:1472
	ds_write_b16_d16_hi v208, v133 offset:1552
	s_waitcnt lgkmcnt(0)
	ds_read_b128 v[212:215], v209
	ds_read_b128 v[216:219], v209 offset:1280
	s_add_u32 s46, s44, s38
	s_addc_u32 s47, s45, 0
	s_waitcnt lgkmcnt(0)
	global_store_dwordx4 v210, v[212:215], s[46:47]
	global_store_dwordx4 v211, v[216:219], s[46:47]
	v_pk_mul_f32 v[128:129], v[28:29], v[156:157] op_sel_hi:[1,0]
	v_pk_mul_f32 v[130:131], v[30:31], v[156:157] op_sel_hi:[1,0]
	v_add_u32_e32 v244, 0x50000, v220
	global_store_dwordx4 v244, v[128:131], s[48:49]
	v_cvt_pk_bf16_f32 v132, v128, v129
	v_cvt_pk_bf16_f32 v133, v130, v131
	ds_write_b16 v208, v132
	ds_write_b16_d16_hi v208, v132 offset:80
	ds_write_b16 v208, v133 offset:160
	ds_write_b16_d16_hi v208, v133 offset:240
	v_pk_mul_f32 v[128:129], v[24:25], v[156:157] op_sel_hi:[1,0]
	v_pk_mul_f32 v[130:131], v[26:27], v[156:157] op_sel_hi:[1,0]
	v_add_u32_e32 v244, 0x50000, v220
	global_store_dwordx4 v244, v[128:131], s[48:49] offset:64
	v_cvt_pk_bf16_f32 v132, v128, v129
	v_cvt_pk_bf16_f32 v133, v130, v131
	ds_write_b16 v208, v132 offset:1280
	ds_write_b16_d16_hi v208, v132 offset:1360
	ds_write_b16 v208, v133 offset:1440
	ds_write_b16_d16_hi v208, v133 offset:1520
	v_pk_mul_f32 v[128:129], v[12:13], v[152:153] op_sel_hi:[1,0]
	v_pk_mul_f32 v[130:131], v[14:15], v[152:153] op_sel_hi:[1,0]
	v_add_u32_e32 v244, 0x58000, v220
	global_store_dwordx4 v244, v[128:131], s[48:49]
	v_cvt_pk_bf16_f32 v132, v128, v129
	v_cvt_pk_bf16_f32 v133, v130, v131
	ds_write_b16 v208, v132 offset:32
	ds_write_b16_d16_hi v208, v132 offset:112
	ds_write_b16 v208, v133 offset:192
	ds_write_b16_d16_hi v208, v133 offset:272
	v_pk_mul_f32 v[128:129], v[8:9], v[152:153] op_sel_hi:[1,0]
	v_pk_mul_f32 v[130:131], v[10:11], v[152:153] op_sel_hi:[1,0]
	v_add_u32_e32 v244, 0x58000, v220
	global_store_dwordx4 v244, v[128:131], s[48:49] offset:64
	v_cvt_pk_bf16_f32 v132, v128, v129
	v_cvt_pk_bf16_f32 v133, v130, v131
	ds_write_b16 v208, v132 offset:1312
	ds_write_b16_d16_hi v208, v132 offset:1392
	ds_write_b16 v208, v133 offset:1472
	ds_write_b16_d16_hi v208, v133 offset:1552
	s_waitcnt lgkmcnt(0)
	ds_read_b128 v[212:215], v209
	ds_read_b128 v[216:219], v209 offset:1280
	s_add_u32 s46, s44, s38
	s_addc_u32 s47, s45, 0
	s_waitcnt lgkmcnt(0)
	global_store_dwordx4 v210, v[212:215], s[46:47] offset:64
	global_store_dwordx4 v211, v[216:219], s[46:47] offset:64
	v_pk_mul_f32 v[128:129], v[52:53], v[164:165] op_sel_hi:[1,0]
	v_pk_mul_f32 v[130:131], v[54:55], v[164:165] op_sel_hi:[1,0]
	v_add_u32_e32 v244, 0x40000, v220
	global_store_dwordx4 v244, v[128:131], s[48:49] offset:512
	v_cvt_pk_bf16_f32 v132, v128, v129
	v_cvt_pk_bf16_f32 v133, v130, v131
	ds_write_b16 v208, v132
	ds_write_b16_d16_hi v208, v132 offset:80
	ds_write_b16 v208, v133 offset:160
	ds_write_b16_d16_hi v208, v133 offset:240
	v_pk_mul_f32 v[128:129], v[48:49], v[164:165] op_sel_hi:[1,0]
	v_pk_mul_f32 v[130:131], v[50:51], v[164:165] op_sel_hi:[1,0]
	v_add_u32_e32 v244, 0x40000, v220
	global_store_dwordx4 v244, v[128:131], s[48:49] offset:576
	v_cvt_pk_bf16_f32 v132, v128, v129
	v_cvt_pk_bf16_f32 v133, v130, v131
	ds_write_b16 v208, v132 offset:1280
	ds_write_b16_d16_hi v208, v132 offset:1360
	ds_write_b16 v208, v133 offset:1440
	ds_write_b16_d16_hi v208, v133 offset:1520
	v_pk_mul_f32 v[128:129], v[36:37], v[160:161] op_sel_hi:[1,0]
	v_pk_mul_f32 v[130:131], v[38:39], v[160:161] op_sel_hi:[1,0]
	v_add_u32_e32 v244, 0x48000, v220
	global_store_dwordx4 v244, v[128:131], s[48:49] offset:512
	v_cvt_pk_bf16_f32 v132, v128, v129
	v_cvt_pk_bf16_f32 v133, v130, v131
	ds_write_b16 v208, v132 offset:32
	ds_write_b16_d16_hi v208, v132 offset:112
	ds_write_b16 v208, v133 offset:192
	ds_write_b16_d16_hi v208, v133 offset:272
	v_pk_mul_f32 v[128:129], v[32:33], v[160:161] op_sel_hi:[1,0]
	v_pk_mul_f32 v[130:131], v[34:35], v[160:161] op_sel_hi:[1,0]
	v_add_u32_e32 v244, 0x48000, v220
	global_store_dwordx4 v244, v[128:131], s[48:49] offset:576
	v_cvt_pk_bf16_f32 v132, v128, v129
	v_cvt_pk_bf16_f32 v133, v130, v131
	ds_write_b16 v208, v132 offset:1312
	ds_write_b16_d16_hi v208, v132 offset:1392
	ds_write_b16 v208, v133 offset:1472
	ds_write_b16_d16_hi v208, v133 offset:1552
	s_waitcnt lgkmcnt(0)
	ds_read_b128 v[212:215], v209
	ds_read_b128 v[216:219], v209 offset:1280
	s_add_u32 s46, s44, s38
	s_addc_u32 s47, s45, 0
	s_add_u32 s46, s46, s100
	s_addc_u32 s47, s47, 0
	s_waitcnt lgkmcnt(0)
	global_store_dwordx4 v210, v[212:215], s[46:47]
	global_store_dwordx4 v211, v[216:219], s[46:47]
	v_pk_mul_f32 v[128:129], v[20:21], v[156:157] op_sel_hi:[1,0]
	v_pk_mul_f32 v[130:131], v[22:23], v[156:157] op_sel_hi:[1,0]
	v_add_u32_e32 v244, 0x50000, v220
	global_store_dwordx4 v244, v[128:131], s[48:49] offset:512
	v_cvt_pk_bf16_f32 v132, v128, v129
	v_cvt_pk_bf16_f32 v133, v130, v131
	ds_write_b16 v208, v132
	ds_write_b16_d16_hi v208, v132 offset:80
	ds_write_b16 v208, v133 offset:160
	ds_write_b16_d16_hi v208, v133 offset:240
	v_pk_mul_f32 v[128:129], v[16:17], v[156:157] op_sel_hi:[1,0]
	v_pk_mul_f32 v[130:131], v[18:19], v[156:157] op_sel_hi:[1,0]
	v_add_u32_e32 v244, 0x50000, v220
	global_store_dwordx4 v244, v[128:131], s[48:49] offset:576
	v_cvt_pk_bf16_f32 v132, v128, v129
	v_cvt_pk_bf16_f32 v133, v130, v131
	ds_write_b16 v208, v132 offset:1280
	ds_write_b16_d16_hi v208, v132 offset:1360
	ds_write_b16 v208, v133 offset:1440
	ds_write_b16_d16_hi v208, v133 offset:1520
	v_pk_mul_f32 v[128:129], v[4:5], v[152:153] op_sel_hi:[1,0]
	v_pk_mul_f32 v[130:131], v[6:7], v[152:153] op_sel_hi:[1,0]
	v_add_u32_e32 v244, 0x58000, v220
	global_store_dwordx4 v244, v[128:131], s[48:49] offset:512
	v_cvt_pk_bf16_f32 v132, v128, v129
	v_cvt_pk_bf16_f32 v133, v130, v131
	ds_write_b16 v208, v132 offset:32
	ds_write_b16_d16_hi v208, v132 offset:112
	ds_write_b16 v208, v133 offset:192
	ds_write_b16_d16_hi v208, v133 offset:272
	v_pk_mul_f32 v[128:129], v[0:1], v[152:153] op_sel_hi:[1,0]
	v_pk_mul_f32 v[130:131], v[2:3], v[152:153] op_sel_hi:[1,0]
	v_add_u32_e32 v244, 0x58000, v220
	global_store_dwordx4 v244, v[128:131], s[48:49] offset:576
	v_cvt_pk_bf16_f32 v132, v128, v129
	v_cvt_pk_bf16_f32 v133, v130, v131
	ds_write_b16 v208, v132 offset:1312
	ds_write_b16_d16_hi v208, v132 offset:1392
	ds_write_b16 v208, v133 offset:1472
	ds_write_b16_d16_hi v208, v133 offset:1552
	s_waitcnt lgkmcnt(0)
	ds_read_b128 v[212:215], v209
	ds_read_b128 v[216:219], v209 offset:1280
	s_add_u32 s46, s44, s38
	s_addc_u32 s47, s45, 0
	s_add_u32 s46, s46, s100
	s_addc_u32 s47, s47, 0
	s_waitcnt lgkmcnt(0)
	global_store_dwordx4 v210, v[212:215], s[46:47] offset:64
	global_store_dwordx4 v211, v[216:219], s[46:47] offset:64
	s_branch .LBB0_586
